# v19 + one static s_setprio 1 for waves 4-7 at the entry of every GEMM phase (s_setprio 0 at the entry of the other phases)
# baseline (speedup 1.0000x reference)
.LBB0_141:
	s_cmp_lt_i32 s84, 2
	s_cselect_b64 s[4:5], -1, 0
	s_cmp_gt_i32 s85, 1
	s_waitcnt lgkmcnt(0)
	s_cselect_b64 s[6:7], -1, 0
	s_and_b64 s[4:5], s[4:5], s[6:7]
	s_andn2_b64 vcc, exec, s[4:5]
	s_cbranch_vccnz .LBB0_215
	s_setprio 0
	v_lshl_or_b32 v2, s72, 9, v0
	s_mov_b32 s3, 0x28000
	s_mov_b64 s[6:7], s[70:71]
	v_cmp_gt_i32_e32 vcc, s3, v2
	s_and_saveexec_b64 s[4:5], vcc
	s_cbranch_execz .LBB0_161
	s_load_dwordx2 s[8:9], s[6:7], 0xb8
	s_lshl_b32 s3, s33, 9
	s_mov_b64 s[6:7], 0
	s_mov_b32 s14, 0x23fff
	s_movk_i32 s15, 0x7ff
	s_waitcnt lgkmcnt(0)
	s_add_u32 s8, s8, 0x43100000
	s_addc_u32 s9, s9, 0
	v_mov_b32_e32 v5, 0
	s_mov_b32 s16, 0x38e38e39
	s_movk_i32 s17, 0x1fff
	s_movk_i32 s18, 0x37ff
	s_movk_i32 s19, 0x3800
	s_movk_i32 s20, 0x2000
	s_movk_i32 s21, 0x800
	s_mov_b32 s26, 0x27fff
	s_branch .LBB0_146

.LBB0_215:
	s_cmp_lt_i32 s84, 3
	s_cselect_b64 s[4:5], -1, 0
	s_cmp_gt_i32 s85, 2
	s_cselect_b64 s[6:7], -1, 0
	s_and_b64 s[4:5], s[4:5], s[6:7]
	s_andn2_b64 vcc, exec, s[4:5]
	s_cbranch_vccnz .LBB0_275
	s_setprio 0
	s_lshl_b32 s3, s72, 6
	s_lshl_b32 s4, s59, 3
	s_add_i32 s4, s3, s4
	s_mov_b64 s[6:7], s[70:71]
	s_mov_b64 s[8:9], s[70:71]
	s_mov_b64 s[10:11], s[70:71]
	s_mov_b64 s[12:13], s[70:71]
	s_mov_b64 s[22:23], s[70:71]
	s_cmpk_gt_i32 s4, 0x3fff
	s_cbranch_scc1 .LBB0_221
	v_mbcnt_lo_u32_b32 v2, -1, 0
	v_mbcnt_hi_u32_b32 v2, -1, v2
	v_and_b32_e32 v3, 64, v2
	v_add_u32_e32 v3, 64, v3
	v_xor_b32_e32 v4, 1, v2
	v_cmp_lt_i32_e32 vcc, v4, v3
	s_load_dwordx2 s[14:15], s[10:11], 0xb8
	s_load_dwordx2 s[18:19], s[6:7], 0x0
	s_load_dwordx2 s[16:17], s[12:13], 0xb8
	s_load_dwordx2 s[20:21], s[8:9], 0x28
	s_load_dwordx2 s[24:25], s[22:23], 0xb8
	v_cndmask_b32_e32 v4, v2, v4, vcc
	v_lshlrev_b32_e32 v82, 2, v4
	v_xor_b32_e32 v4, 2, v2
	v_cmp_lt_i32_e32 vcc, v4, v3
	s_waitcnt lgkmcnt(0)
	s_add_u32 s3, s14, 0x600000
	s_addc_u32 s14, s15, 0
	v_cndmask_b32_e32 v4, v2, v4, vcc
	v_lshlrev_b32_e32 v83, 2, v4
	v_xor_b32_e32 v4, 4, v2
	v_cmp_lt_i32_e32 vcc, v4, v3
	s_add_u32 s15, s16, 0x602000
	s_addc_u32 s16, s17, 0
	v_cndmask_b32_e32 v4, v2, v4, vcc
	v_lshlrev_b32_e32 v84, 2, v4
	v_xor_b32_e32 v4, 8, v2
	v_cmp_lt_i32_e32 vcc, v4, v3
	v_mov_b32_e32 v5, 0
	s_ashr_i32 s5, s4, 31
	v_cndmask_b32_e32 v4, v2, v4, vcc
	v_lshlrev_b32_e32 v85, 2, v4
	v_xor_b32_e32 v4, 16, v2
	v_cmp_lt_i32_e32 vcc, v4, v3
	s_lshl_b32 s6, s33, 6
	v_mov_b32_e32 v9, v5
	v_cndmask_b32_e32 v4, v2, v4, vcc
	v_lshlrev_b32_e32 v86, 2, v4
	v_xor_b32_e32 v4, 32, v2
	v_cmp_lt_i32_e32 vcc, v4, v3
	s_lshl_b64 s[8:9], s[4:5], 13
	s_add_u32 s8, s18, s8
	v_cndmask_b32_e32 v2, v2, v4, vcc
	v_lshlrev_b32_e32 v87, 2, v2
	v_lshlrev_b32_e32 v2, 2, v1
	v_or_b32_e32 v6, 0x400, v2
	v_lshlrev_b32_e32 v8, 2, v6
	v_lshl_add_u64 v[36:37], s[20:21], 0, v[8:9]
	v_or_b32_e32 v8, 0x500, v2
	v_lshlrev_b32_e32 v4, 4, v1
	v_lshlrev_b32_e32 v10, 2, v8
	v_mov_b32_e32 v11, v5
	s_addc_u32 s9, s19, s9
	s_ashr_i32 s7, s6, 31
	v_lshl_add_u64 v[38:39], s[20:21], 0, v[10:11]
	v_or_b32_e32 v10, 0x600, v2
	v_lshl_add_u64 v[44:45], s[8:9], 0, v[4:5]
	s_lshl_b64 s[8:9], s[6:7], 13
	s_lshl_b64 s[10:11], s[4:5], 12
	v_lshlrev_b32_e32 v12, 2, v10
	v_mov_b32_e32 v13, v5
	s_add_u32 s10, s24, s10
	v_lshl_add_u64 v[34:35], s[20:21], 0, v[4:5]
	v_lshl_add_u64 v[40:41], s[20:21], 0, v[12:13]
	v_or_b32_e32 v12, 0x700, v2
	v_lshlrev_b32_e32 v4, 3, v1
	s_addc_u32 s11, s25, s11
	v_lshlrev_b32_e32 v14, 2, v12
	v_mov_b32_e32 v15, v5
	v_lshl_add_u64 v[4:5], s[10:11], 0, v[4:5]
	s_mov_b64 s[10:11], 0x18000800
	v_lshl_add_u64 v[42:43], s[20:21], 0, v[14:15]
	v_lshl_add_u64 v[46:47], v[4:5], 0, s[10:11]
	s_lshl_b64 s[10:11], s[6:7], 12
	v_lshlrev_b32_e32 v88, 2, v2
	v_lshlrev_b32_e32 v89, 2, v6
	v_lshlrev_b32_e32 v90, 2, v8
	v_lshlrev_b32_e32 v91, 2, v10
	v_lshlrev_b32_e32 v92, 2, v12
	s_movk_i32 s5, 0x1000
	v_mov_b32_e32 v93, 0x358637bd
	s_mov_b64 s[12:13], 0x1000

.LBB0_275:
	s_cmp_lt_i32 s84, 4
	s_cselect_b64 s[4:5], -1, 0
	s_cmp_gt_i32 s85, 3
	s_cselect_b64 s[6:7], -1, 0
	s_and_b64 s[4:5], s[4:5], s[6:7]
	s_andn2_b64 vcc, exec, s[4:5]
	s_cbranch_vccnz .LBB0_346
	v_readfirstlane_b32 s98, v0
	s_nop 3
	s_bitcmp1_b32 s98, 8
	s_cbranch_scc0 .Lsprio_skip_4
	s_setprio 1
.Lsprio_skip_4:
	s_mov_b64 s[6:7], s[70:71]
	s_mov_b64 s[8:9], s[70:71]
	s_mov_b64 s[4:5], s[70:71]
	s_cmpk_gt_i32 s2, 0xaff
	v_readfirstlane_b32 s13, v0
	s_cbranch_scc1 .LBB0_292
	s_load_dwordx2 s[10:11], s[6:7], 0xb8
	s_load_dwordx2 s[14:15], s[8:9], 0xb8
	v_lshrrev_b32_e32 v2, 5, v0
	v_lshrrev_b32_e32 v4, 1, v0
	v_and_b32_e32 v2, 4, v2
	v_bfe_u32 v3, v0, 2, 2
	v_and_b32_e32 v13, 24, v4
	s_waitcnt lgkmcnt(0)
	s_add_u32 s40, s10, 0x18000000
	v_or3_b32 v2, v2, v3, v13
	v_lshlrev_b32_e32 v3, 4, v0
	s_addc_u32 s41, s11, 0
	v_or_b32_e32 v10, 0x2000, v3
	s_add_u32 s42, s14, 0x2400000
	v_lshrrev_b32_e32 v4, 7, v10
	s_movk_i32 s6, 0x60
	s_addc_u32 s43, s15, 0
	v_and_or_b32 v5, v4, s6, v2
	v_bfe_u32 v14, v0, 2, 4
	s_movk_i32 s6, 0x70
	s_ashr_i32 s45, s2, 31
	v_and_or_b32 v4, v4, s6, v14
	s_lshr_b32 s6, s45, 29
	s_add_i32 s6, s2, s6
	s_lshr_b32 s3, s13, 6
	s_ashr_i32 s7, s6, 3
	s_and_b32 s6, s6, -8
	s_lshr_b32 s14, s13, 8
	s_lshl_b32 s44, s3, 10
	s_sub_i32 s6, s2, s6
	s_cmp_lt_i32 s6, 0
	s_movk_i32 s46, 0x161
	s_cselect_b32 s8, s46, 0x160
	s_mul_i32 s6, s6, s8
	s_add_i32 s6, s6, s7
	s_mul_hi_i32 s7, s6, 0x2e8ba2e9
	s_lshr_b32 s8, s7, 31
	s_ashr_i32 s7, s7, 6
	s_add_i32 s7, s7, s8
	s_lshl_b32 s8, s7, 3
	s_mulk_i32 s7, 0x160
	s_sub_i32 s6, s6, s7
	s_sext_i32_i16 s7, s6
	s_bfe_u32 s7, s7, 0x3001c
	s_add_i32 s7, s6, s7
	s_sext_i32_i16 s9, s7
	s_and_b32 s7, s7, 0xfff8
	s_sub_i32 s6, s6, s7
	s_sext_i32_i16 s6, s6
	v_and_b32_e32 v6, 32, v0
	s_lshr_b32 s12, s9, 3
	s_add_i32 s30, s8, s6
	v_bitop3_b32 v11, v3, v6, 48 bitop3:0x6c
	v_and_b32_e32 v12, 64, v0
	s_ashr_i32 s31, s30, 31
	s_bfe_i64 s[8:9], s[12:13], 0x100000
	v_or_b32_e32 v3, v11, v12
	s_lshl_b64 s[6:7], s[30:31], 20
	s_lshl_b64 s[8:9], s[8:9], 20
	v_lshl_or_b32 v132, v4, 12, v3
	v_lshrrev_b32_e32 v4, 3, v0
	s_add_u32 s36, s42, s8
	v_and_or_b32 v2, v4, 32, v2
	s_addc_u32 s37, s43, s9
	s_add_i32 s31, s44, 0
	v_lshl_or_b32 v134, v2, 12, v3
	s_add_i32 m0, s31, 0x10000
	v_lshl_or_b32 v130, v5, 12, v3
	global_load_lds_dwordx4 v134, s[36:37]
	s_add_i32 m0, s31, 0x12000
	s_add_u32 s8, s36, 0x80000
	global_load_lds_dwordx4 v130, s[36:37]
	s_addc_u32 s9, s37, 0
	s_add_i32 m0, s31, 0x14000
	v_and_or_b32 v2, v4, 48, v14
	global_load_lds_dwordx4 v134, s[8:9]
	s_add_i32 m0, s31, 0x16000
	s_add_u32 s34, s40, s6
	s_addc_u32 s35, s41, s7
	s_add_i32 s47, s31, 0x2000
	v_lshl_or_b32 v136, v2, 12, v3
	global_load_lds_dwordx4 v130, s[8:9]
	s_mov_b32 m0, s31
	s_add_u32 s6, s34, 0x80000
	global_load_lds_dwordx4 v136, s[34:35]
	s_mov_b32 m0, s47
	s_addc_u32 s7, s35, 0
	s_add_i32 s48, s31, 0x4000
	global_load_lds_dwordx4 v132, s[34:35]
	s_mov_b32 m0, s48
	s_add_i32 s49, s31, 0x6000
	global_load_lds_dwordx4 v136, s[6:7]
	s_mov_b32 m0, s49
	s_load_dwordx2 s[4:5], s[4:5], 0xb8
	global_load_lds_dwordx4 v132, s[6:7]
	v_mov_b32_e32 v135, 0
	v_mov_b32_e32 v131, v135
	v_mov_b32_e32 v137, v135
	v_mov_b32_e32 v133, v135
	s_cmp_eq_u32 s14, 1
	s_mov_b32 s50, 0
	v_lshl_add_u64 v[8:9], s[36:37], 0, v[134:135]
	v_lshl_add_u64 v[6:7], s[36:37], 0, v[130:131]
	v_lshl_add_u64 v[2:3], s[34:35], 0, v[136:137]
	s_cselect_b64 s[6:7], -1, 0
	s_cmp_lg_u32 s14, 1
	v_lshl_add_u64 v[4:5], s[34:35], 0, v[132:133]
	s_cbranch_scc1 .LBB0_279
	s_barrier

.LBB0_346:
	s_cmp_lt_i32 s84, 5
	s_cselect_b64 s[4:5], -1, 0
	s_cmp_gt_i32 s85, 4
	s_cselect_b64 s[6:7], -1, 0
	s_and_b64 s[4:5], s[4:5], s[6:7]
	s_andn2_b64 vcc, exec, s[4:5]
	s_cbranch_vccnz .LBB0_453
	v_readfirstlane_b32 s98, v0
	s_nop 3
	s_bitcmp1_b32 s98, 8
	s_cbranch_scc0 .Lsprio_skip_5
	s_setprio 1
.Lsprio_skip_5:
	s_and_b32 s3, s2, 7
	s_ashr_i32 s14, s33, 6
	s_mul_i32 s48, s14, s3
	s_ashr_i32 s3, s2, 6
	s_add_i32 s48, s48, s3
	s_mov_b64 s[8:9], s[70:71]
	s_mov_b64 s[34:35], s[70:71]
	s_mov_b64 s[4:5], s[70:71]
	s_mov_b64 s[6:7], s[70:71]
	s_mov_b64 s[10:11], s[70:71]
	s_mov_b64 s[12:13], s[70:71]
	s_mov_b64 s[22:23], s[70:71]
	s_mov_b64 s[24:25], s[70:71]
	s_mov_b64 s[26:27], s[70:71]
	s_mov_b64 s[28:29], s[70:71]
	s_mov_b64 s[30:31], s[70:71]
	s_cmp_gt_i32 s48, 63
	v_readfirstlane_b32 s14, v0
	s_cbranch_scc1 .LBB0_399
	v_lshrrev_b32_e32 v2, 5, v0
	v_lshrrev_b32_e32 v4, 1, v0
	v_and_b32_e32 v2, 4, v2
	v_bfe_u32 v3, v0, 2, 2
	v_and_b32_e32 v4, 24, v4
	v_lshlrev_b32_e32 v210, 4, v0
	v_or3_b32 v2, v2, v3, v4
	v_bfe_u32 v3, v0, 3, 25
	v_and_b32_e32 v5, 32, v0
	s_load_dwordx2 s[16:17], s[8:9], 0xb8
	s_load_dwordx2 s[18:19], s[34:35], 0xb8
	v_or_b32_e32 v3, 64, v3
	s_movk_i32 s8, 0x60
	v_bitop3_b32 v10, v210, v5, 48 bitop3:0x6c
	v_and_b32_e32 v11, 64, v0
	v_and_or_b32 v4, v3, s8, v2
	v_or_b32_e32 v5, v10, v11
	v_mul_u32_u24_e32 v4, 0x1600, v4
	v_lshrrev_b32_e32 v5, 1, v5
	v_or_b32_e32 v4, v4, v5
	v_lshlrev_b32_e32 v146, 1, v4
	v_bfe_u32 v4, v0, 2, 4
	s_movk_i32 s8, 0x70
	s_waitcnt lgkmcnt(0)
	s_add_u32 s49, s16, 0x20000000
	v_and_or_b32 v3, v3, s8, v4
	s_addc_u32 s50, s17, 0
	s_lshr_b32 s17, s14, 6
	s_bfe_u32 s15, s2, 0x30003
	v_mul_u32_u24_e32 v12, 0x1600, v3
	s_lshr_b32 s16, s14, 8
	s_lshl_b32 s3, s17, 10
	v_or_b32_e32 v3, v12, v5
	s_mul_i32 s8, s15, 0x2c0000
	v_lshlrev_b32_e32 v148, 1, v3
	v_lshrrev_b32_e32 v3, 3, v0
	s_add_u32 s18, s18, s8
	v_and_or_b32 v2, v3, 32, v2
	s_addc_u32 s19, s19, 0
	v_mul_u32_u24_e32 v2, 0x1600, v2
	s_add_u32 s8, s18, 0xd400000
	v_or_b32_e32 v2, v2, v5
	s_addc_u32 s9, s19, 0
	s_add_i32 s51, s3, 0
	v_lshlrev_b32_e32 v150, 1, v2
	s_add_i32 m0, s51, 0x10000
	v_and_or_b32 v2, v3, 48, v4
	global_load_lds_dwordx4 v150, s[8:9]
	s_add_i32 m0, s51, 0x12000
	s_add_u32 s18, s18, 0xd560000
	global_load_lds_dwordx4 v146, s[8:9]
	s_addc_u32 s19, s19, 0
	s_add_i32 m0, s51, 0x14000
	s_mul_i32 s21, s48, 0x2c0000
	global_load_lds_dwordx4 v150, s[18:19]
	s_add_i32 m0, s51, 0x16000
	v_mul_u32_u24_e32 v13, 0x1600, v2
	s_mul_hi_i32 s20, s48, 0x2c0000
	s_add_u32 s34, s49, s21
	v_or_b32_e32 v2, v5, v13
	s_addc_u32 s35, s50, s20
	s_add_i32 s52, s51, 0x2000
	v_lshlrev_b32_e32 v152, 1, v2
	global_load_lds_dwordx4 v146, s[18:19]
	s_mov_b32 m0, s51
	s_add_u32 s18, s34, 0x160000
	global_load_lds_dwordx4 v152, s[34:35]
	s_mov_b32 m0, s52
	s_addc_u32 s19, s35, 0
	s_add_i32 s53, s51, 0x4000
	global_load_lds_dwordx4 v148, s[34:35]
	s_mov_b32 m0, s53
	s_add_i32 s54, s51, 0x6000
	global_load_lds_dwordx4 v152, s[18:19]
	s_mov_b32 m0, s54
	v_mov_b32_e32 v151, 0
	global_load_lds_dwordx4 v148, s[18:19]
	s_load_dwordx2 s[40:41], s[4:5], 0x0
	s_load_dwordx2 s[36:37], s[6:7], 0xb0
	s_load_dwordx2 s[42:43], s[10:11], 0xb8
	s_nop 0
	s_load_dwordx2 s[6:7], s[12:13], 0xb8
	s_load_dwordx2 s[4:5], s[22:23], 0xb8
	s_load_dwordx2 s[10:11], s[24:25], 0xb8
	s_load_dwordx2 s[38:39], s[26:27], 0xb8
	s_nop 0
	s_load_dwordx2 s[28:29], s[28:29], 0xb8
	s_nop 0
	s_load_dwordx2 s[26:27], s[30:31], 0xb8
	v_mov_b32_e32 v147, v151
	v_mov_b32_e32 v153, v151
	v_mov_b32_e32 v149, v151
	s_cmp_eq_u32 s16, 1
	s_mov_b32 s55, 0
	v_lshl_add_u64 v[8:9], s[8:9], 0, v[150:151]
	v_lshl_add_u64 v[6:7], s[8:9], 0, v[146:147]
	v_lshl_add_u64 v[2:3], s[34:35], 0, v[152:153]
	s_cselect_b64 s[12:13], -1, 0
	s_cmp_lg_u32 s16, 1
	v_lshl_add_u64 v[4:5], s[34:35], 0, v[148:149]
	s_cbranch_scc1 .LBB0_350
	s_barrier

.LBB0_453:
	s_cmp_lt_i32 s84, 7
	s_cselect_b64 s[4:5], -1, 0
	s_cmp_gt_i32 s85, 6
	s_cselect_b64 s[6:7], -1, 0
	s_and_b64 s[4:5], s[4:5], s[6:7]
	s_andn2_b64 vcc, exec, s[4:5]
	s_cbranch_vccnz .LBB0_562
	v_readfirstlane_b32 s98, v0
	s_nop 3
	s_bitcmp1_b32 s98, 8
	s_cbranch_scc0 .Lsprio_skip_7
	s_setprio 1
.Lsprio_skip_7:
	s_cmpk_lt_i32 s2, 0xc00
	s_mov_b64 s[26:27], s[70:71]
	s_mov_b64 s[28:29], s[70:71]
	s_mov_b64 s[4:5], s[70:71]
	s_mov_b64 s[8:9], s[70:71]
	s_mov_b64 s[10:11], s[70:71]
	s_mov_b64 s[12:13], s[70:71]
	s_mov_b64 s[22:23], s[70:71]
	s_mov_b64 s[24:25], s[70:71]
	s_cselect_b64 s[30:31], -1, 0
	s_cmpk_gt_i32 s2, 0xbff
	v_readfirstlane_b32 s3, v0
	s_cbranch_scc0 .LBB0_457
	s_andn2_b64 vcc, exec, s[30:31]
	s_cbranch_vccz .LBB0_458

.LBB0_562:
	s_cmp_lt_i32 s84, 8
	s_cselect_b64 s[4:5], -1, 0
	s_cmp_gt_i32 s85, 7
	s_cselect_b64 s[6:7], -1, 0
	s_and_b64 s[4:5], s[4:5], s[6:7]
	s_andn2_b64 vcc, exec, s[4:5]
	s_cbranch_vccnz .LBB0_633
	s_setprio 0
	s_mov_b64 s[4:5], s[70:71]
	s_mov_b64 s[6:7], s[70:71]
	s_mov_b64 s[8:9], s[70:71]
	s_mov_b64 s[10:11], s[70:71]
	s_mov_b64 s[12:13], s[70:71]
	s_cmpk_gt_i32 s72, 0xff
	s_cbranch_scc1 .LBB0_579
	s_load_dwordx2 s[26:27], s[4:5], 0xb8
	s_load_dwordx2 s[30:31], s[6:7], 0xb8
	s_load_dwordx2 s[36:37], s[8:9], 0xb8
	s_load_dwordx2 s[28:29], s[10:11], 0xb8
	s_load_dwordx2 s[34:35], s[12:13], 0xb8
	s_waitcnt lgkmcnt(0)
	s_add_u32 s10, s26, 0x20000000
	s_addc_u32 s11, s27, 0
	s_add_u32 s12, s30, 0x24000000
	s_addc_u32 s13, s31, 0
	s_add_u32 s22, s36, 0x2b000000
	s_addc_u32 s23, s37, 0
	s_lshr_b32 s4, s58, 8
	v_and_b32_e32 v2, 15, v0
	s_lshl_b32 s7, s4, 5
	s_movk_i32 s6, 0x210
	v_or_b32_e32 v6, s7, v2
	s_bfe_u32 s3, s58, 0x20006
	v_mul_lo_u32 v6, v6, s6
	s_add_i32 s14, 0, 0x10800
	v_lshrrev_b32_e32 v3, 4, v1
	s_lshl_b32 s5, s3, 4
	v_add_u32_e32 v10, 0, v6
	v_mov_b32_e32 v6, s14
	v_bfe_u32 v4, v0, 2, 2
	v_or_b32_e32 v5, s5, v2
	v_mad_u32_u24 v2, v2, s6, v6
	v_lshl_or_b32 v6, v3, 2, s7
	v_or_b32_e32 v7, v6, v4
	s_movk_i32 s7, 0x110
	v_mul_lo_u32 v7, v7, s7
	s_add_i32 s8, 0, 0x18c00
	v_lshlrev_b32_e32 v3, 3, v3
	v_lshrrev_b32_e32 v104, 3, v0
	v_add_u32_e32 v22, 1, v5
	v_add_u32_e32 v12, s8, v7
	v_lshlrev_b32_e32 v7, 3, v0
	v_or_b32_e32 v4, v3, v4
	v_cvt_f32_ubyte0_e32 v103, v22
	v_xor_b32_e32 v22, 63, v104
	v_and_b32_e32 v13, 24, v7
	v_mul_u32_u24_e32 v7, 0x210, v4
	v_cvt_f32_ubyte0_e32 v105, v22
	v_sub_u32_e32 v22, v5, v6
	v_add3_u32 v14, 0, v7, v13
	v_mov_b32_e32 v7, s8
	v_sub_u32_e32 v23, 0, v22
	v_mad_u32_u24 v15, v4, s7, v7
	v_mad_u32_u24 v20, v104, s7, v7
	v_bitop3_b32 v7, s5, v0, 15 bitop3:7
	v_max_i32_e32 v23, v22, v23
	v_add_u32_e32 v23, v23, v7
	v_xad_u32 v6, v6, -1, v5
	v_cvt_f32_i32_e32 v146, v23
	v_sub_u32_e32 v23, 0, v6
	v_max_i32_e32 v6, v6, v23
	v_add_u32_e32 v6, v6, v7
	v_cvt_f32_i32_e32 v147, v6
	v_add_u32_e32 v6, -2, v22
	v_sub_u32_e32 v23, 2, v22
	v_max_i32_e32 v6, v6, v23
	v_add_u32_e32 v6, v6, v7
	v_cvt_f32_i32_e32 v148, v6
	v_add_u32_e32 v6, -3, v22
	v_sub_u32_e32 v23, 3, v22
	v_max_i32_e32 v6, v6, v23
	v_add_u32_e32 v6, v6, v7
	v_cvt_f32_i32_e32 v149, v6
	v_add_u32_e32 v6, -16, v22
	v_sub_u32_e32 v23, 16, v22
	v_max_i32_e32 v6, v6, v23
	v_add_u32_e32 v6, v6, v7
	v_cvt_f32_i32_e32 v150, v6
	v_subrev_u32_e32 v6, 17, v22
	v_sub_u32_e32 v23, 17, v22
	v_max_i32_e32 v6, v6, v23
	v_add_u32_e32 v6, v6, v7
	v_cvt_f32_i32_e32 v151, v6
	v_subrev_u32_e32 v6, 18, v22
	v_sub_u32_e32 v23, 18, v22
	v_max_i32_e32 v6, v6, v23
	v_add_u32_e32 v6, v6, v7
	v_and_b32_e32 v9, 48, v0
	s_and_b32 s17, s58, 0xffffffc0
	v_and_b32_e32 v4, 7, v0
	v_cvt_f32_i32_e32 v152, v6
	v_subrev_u32_e32 v6, 19, v22
	v_sub_u32_e32 v22, 19, v22
	v_add_u32_e32 v11, v2, v9
	v_add_u32_e32 v16, s17, v2
	v_and_b32_e32 v2, 31, v0
	v_lshlrev_b32_e32 v21, 4, v4
	v_max_i32_e32 v6, v6, v22
	v_lshrrev_b32_e32 v102, 5, v0
	v_lshlrev_b32_e32 v19, 4, v2
	v_mov_b32_e32 v107, 0
	v_add_u32_e32 v6, v6, v7
	v_lshl_or_b32 v106, v104, 13, v21
	v_cvt_f32_i32_e32 v153, v6
	v_lshl_add_u64 v[6:7], s[36:37], 0, v[106:107]
	v_lshl_or_b32 v106, v102, 12, v19
	s_lshl_b32 s3, s3, 12
	v_lshl_add_u32 v155, v0, 4, s14
	s_mov_b64 s[14:15], 0x2b100000
	v_lshl_add_u64 v[110:111], s[26:27], 0, v[106:107]
	v_lshl_add_u64 v[112:113], s[30:31], 0, v[106:107]
	v_lshlrev_b32_e32 v106, 9, v5
	s_add_i32 s3, s3, 0
	v_lshl_add_u64 v[108:109], v[6:7], 0, s[14:15]
	v_lshl_add_u64 v[6:7], s[34:35], 0, v[106:107]
	s_mov_b64 s[14:15], 0x1b00000
	s_and_b32 s16, s58, 0xffffff00
	s_add_i32 s3, s3, 0x1d000
	v_lshl_add_u64 v[114:115], v[6:7], 0, s[14:15]
	v_lshrrev_b32_e32 v6, 1, v9
	v_lshlrev_b32_e32 v2, 3, v2
	s_cmp_eq_u32 s4, 1
	v_lshl_or_b32 v106, v5, 13, v6
	v_mad_u32_u24 v8, v5, s6, 0
	v_lshlrev_b32_e32 v17, 2, v1
	v_mad_u32_u24 v18, v102, s6, 0
	v_lshlrev_b32_e32 v4, 3, v4
	s_cselect_b64 s[4:5], -1, 0
	s_cmpk_lt_u32 s58, 0x100
	v_lshl_add_u64 v[6:7], s[28:29], 0, v[106:107]
	s_mov_b64 s[14:15], 0x3b000040
	v_lshlrev_b32_e32 v106, 1, v2
	v_mbcnt_lo_u32_b32 v2, -1, 0
	s_mov_b32 s25, 0
	s_cselect_b64 s[6:7], -1, 0
	v_cmp_gt_u32_e64 s[8:9], 16, v1
	v_or_b32_e32 v154, 0xfffffe00, v0
	v_lshl_add_u64 v[116:117], v[6:7], 0, s[14:15]
	s_mov_b32 s14, 0xc2fc0000
	s_mov_b32 s15, 0x800000
	s_movk_i32 s20, 0x63f
	s_mov_b32 s21, 0x10000
	s_mov_b32 s36, 0x20000
	s_mov_b32 s37, 0x30000
	v_lshlrev_b32_e32 v118, 1, v4
	s_mov_b32 s38, 0x40000
	s_mov_b32 s39, 0x50000
	s_mov_b32 s40, 0x60000
	s_mov_b32 s41, 0x70000
	s_mov_b32 s42, 0x80000
	v_add_u32_e32 v156, v8, v9
	v_add_u32_e32 v157, v10, v9
	v_add_u32_e32 v158, s16, v11
	v_add_u32_e32 v159, v12, v13
	v_add_u32_e32 v160, s17, v14
	v_add_u32_e32 v161, v15, v13
	v_add_u32_e32 v163, v16, v3
	s_mov_b64 s[26:27], 0x80000
	s_mov_b64 s[28:29], 0x8000
	v_mov_b32_e32 v164, 0x42800000
	v_mov_b32_e32 v165, 0x42000000
	v_mov_b32_e32 v172, v107
	v_mov_b32_e32 v173, v107
	v_mov_b32_e32 v174, v107
	v_mov_b32_e32 v175, v107
	v_not_b32_e32 v166, 63
	v_add_u32_e32 v167, v18, v19
	v_add_u32_e32 v168, v20, v21
	v_add_u32_e32 v169, s3, v17
	v_mbcnt_hi_u32_b32 v170, -1, v2
	v_xor_b32_e32 v240, 16, v170
	v_xor_b32_e32 v241, 32, v170
	v_lshlrev_b32_e32 v240, 2, v240
	v_lshlrev_b32_e32 v241, 2, v241
	s_mov_b32 s43, s72
	s_branch .LBB0_566

.LBB0_633:
	s_cmp_lt_i32 s84, 9
	s_cselect_b64 s[4:5], -1, 0
	s_cmp_gt_i32 s85, 8
	s_cselect_b64 s[6:7], -1, 0
	s_and_b64 s[4:5], s[4:5], s[6:7]
	s_andn2_b64 vcc, exec, s[4:5]
	s_cbranch_vccnz .LBB0_691
	s_setprio 0
	s_lshl_b32 s3, s72, 3
	s_add_i32 s4, s3, s59
	s_mov_b64 s[6:7], s[70:71]
	s_mov_b64 s[8:9], s[70:71]
	s_mov_b64 s[10:11], s[70:71]
	s_mov_b64 s[12:13], s[70:71]
	s_cmpk_gt_i32 s4, 0x3fff
	s_cbranch_scc1 .LBB0_637
	s_load_dwordx2 s[14:15], s[6:7], 0xb8
	s_load_dwordx2 s[16:17], s[8:9], 0xb8
	s_load_dwordx2 s[18:19], s[12:13], 0x48
	s_load_dwordx2 s[20:21], s[10:11], 0xb8
	s_ashr_i32 s5, s4, 31
	s_lshl_b32 s6, s33, 3
	s_lshl_b64 s[12:13], s[4:5], 13
	s_waitcnt lgkmcnt(0)
	s_add_u32 s8, s16, s12
	s_addc_u32 s9, s17, s13
	s_ashr_i32 s7, s6, 31
	v_lshlrev_b32_e32 v50, 5, v1
	v_mov_b32_e32 v51, 0
	s_lshl_b64 s[10:11], s[6:7], 13
	v_or_b32_e32 v2, 0x1000, v50
	v_mov_b32_e32 v3, v51
	s_add_u32 s12, s14, s12
	v_lshl_add_u64 v[54:55], s[18:19], 0, v[2:3]
	v_or_b32_e32 v2, 0x1800, v50
	s_addc_u32 s13, s15, s13
	s_lshl_b64 s[14:15], s[4:5], 9
	v_lshl_add_u64 v[56:57], s[18:19], 0, v[2:3]
	v_or_b32_e32 v2, 0x2000, v50
	s_add_u32 s3, s20, s14
	v_lshl_add_u64 v[58:59], s[18:19], 0, v[2:3]
	v_or_b32_e32 v2, 0x2800, v50
	s_addc_u32 s5, s21, s15
	v_lshl_add_u64 v[52:53], s[18:19], 0, v[50:51]
	v_lshl_add_u64 v[60:61], s[18:19], 0, v[2:3]
	v_or_b32_e32 v2, 0x3000, v50
	v_or_b32_e32 v50, 0x3800, v50
	s_add_u32 s22, s3, 0x1b00000
	v_lshl_add_u64 v[62:63], s[18:19], 0, v[2:3]
	v_lshl_add_u64 v[64:65], s[18:19], 0, v[50:51]
	v_lshlrev_b32_e32 v50, 4, v1
	s_addc_u32 s23, s5, 0
	s_lshl_b64 s[24:25], s[6:7], 9
	s_mov_b32 s26, 0x3b000000
	s_mov_b32 s3, 0x33000000
	s_mov_b32 s5, 0x3b001000
	s_mov_b32 s7, 0x33001000

.LBB0_691:
	s_cmp_lt_i32 s84, 10
	s_cselect_b64 s[4:5], -1, 0
	s_cmp_gt_i32 s85, 9
	s_cselect_b64 s[6:7], -1, 0
	s_and_b64 s[4:5], s[4:5], s[6:7]
	s_andn2_b64 vcc, exec, s[4:5]
	s_cbranch_vccnz .LBB0_796
	v_readfirstlane_b32 s98, v0
	s_nop 3
	s_bitcmp1_b32 s98, 8
	s_cbranch_scc0 .Lsprio_skip_10
	s_setprio 1
.Lsprio_skip_10:
	s_and_b32 s3, s2, 7
	s_ashr_i32 s8, s33, 6
	s_mul_i32 s3, s8, s3
	s_ashr_i32 s8, s2, 6
	s_add_i32 s8, s3, s8
	s_mov_b64 s[10:11], s[70:71]
	s_mov_b64 s[12:13], s[70:71]
	s_mov_b64 s[4:5], s[70:71]
	s_mov_b64 s[6:7], s[70:71]
	s_mov_b64 s[22:23], s[70:71]
	s_mov_b64 s[24:25], s[70:71]
	s_mov_b64 s[26:27], s[70:71]
	s_mov_b64 s[28:29], s[70:71]
	s_mov_b64 s[30:31], s[70:71]
	s_mov_b64 s[34:35], s[70:71]
	s_mov_b64 s[36:37], s[70:71]
	s_cmp_gt_i32 s8, 63
	v_readfirstlane_b32 s3, v0
	s_cbranch_scc1 .LBB0_742
	s_load_dwordx2 s[14:15], s[10:11], 0xb8
	s_load_dwordx2 s[18:19], s[12:13], 0xb8
	v_lshlrev_b32_e32 v210, 4, v0
	v_lshrrev_b32_e32 v2, 5, v0
	v_lshrrev_b32_e32 v4, 1, v0
	v_and_b32_e32 v2, 4, v2
	v_bfe_u32 v3, v0, 2, 2
	v_and_b32_e32 v4, 24, v4
	v_or_b32_e32 v10, 0x2000, v210
	v_or3_b32 v2, v2, v3, v4
	v_lshrrev_b32_e32 v3, 7, v10
	s_movk_i32 s9, 0x60
	s_waitcnt lgkmcnt(0)
	s_add_u32 s52, s14, 0x33000000
	v_and_or_b32 v4, v3, s9, v2
	v_bfe_u32 v13, v0, 2, 4
	s_movk_i32 s9, 0x70
	s_addc_u32 s53, s15, 0
	s_lshr_b32 s16, s3, 6
	s_bfe_u32 s14, s2, 0x30003
	v_and_or_b32 v3, v3, s9, v13
	s_ashr_i32 s9, s8, 31
	s_lshr_b32 s15, s3, 8
	s_lshl_b32 s54, s16, 10
	v_and_b32_e32 v5, 32, v0
	s_lshl_b64 s[12:13], s[8:9], 21
	s_lshl_b32 s9, s14, 21
	v_bitop3_b32 v11, v210, v5, 48 bitop3:0x6c
	v_and_b32_e32 v12, 64, v0
	s_add_u32 s17, s18, s9
	v_or_b32_e32 v5, v11, v12
	s_addc_u32 s19, s19, 0
	v_lshl_or_b32 v148, v3, 13, v5
	v_lshrrev_b32_e32 v3, 3, v0
	s_add_u32 s10, s17, 0x15c00000
	v_and_or_b32 v2, v3, 32, v2
	s_addc_u32 s11, s19, 0
	s_add_i32 s9, s54, 0
	v_lshl_or_b32 v150, v2, 13, v5
	s_add_i32 m0, s9, 0x10000
	v_lshl_or_b32 v146, v4, 13, v5
	global_load_lds_dwordx4 v150, s[10:11]
	s_add_i32 m0, s9, 0x12000
	s_add_u32 s18, s17, 0x15d00000
	global_load_lds_dwordx4 v146, s[10:11]
	s_addc_u32 s19, s19, 0
	s_add_i32 m0, s9, 0x14000
	v_and_or_b32 v2, v3, 48, v13
	global_load_lds_dwordx4 v150, s[18:19]
	s_add_i32 m0, s9, 0x16000
	s_add_u32 s12, s52, s12
	s_addc_u32 s13, s53, s13
	s_add_i32 s55, s9, 0x2000
	v_lshl_or_b32 v152, v2, 13, v5
	global_load_lds_dwordx4 v146, s[18:19]
	s_mov_b32 m0, s9
	s_add_u32 s18, s12, 0x100000
	global_load_lds_dwordx4 v152, s[12:13]
	s_mov_b32 m0, s55
	s_addc_u32 s19, s13, 0
	s_add_i32 s56, s9, 0x4000
	global_load_lds_dwordx4 v148, s[12:13]
	s_mov_b32 m0, s56
	s_add_i32 s57, s9, 0x6000
	global_load_lds_dwordx4 v152, s[18:19]
	s_mov_b32 m0, s57
	v_mov_b32_e32 v151, 0
	global_load_lds_dwordx4 v148, s[18:19]
	s_load_dwordx2 s[42:43], s[4:5], 0xb0
	s_load_dwordx2 s[38:39], s[6:7], 0xb0
	s_load_dwordx2 s[44:45], s[22:23], 0xb8
	s_nop 0
	s_load_dwordx2 s[6:7], s[24:25], 0xb8
	s_load_dwordx2 s[4:5], s[26:27], 0xb8
	s_load_dwordx2 s[22:23], s[28:29], 0xb8
	s_load_dwordx2 s[40:41], s[30:31], 0xb8
	s_nop 0
	s_load_dwordx2 s[34:35], s[34:35], 0xb8
	s_nop 0
	s_load_dwordx2 s[30:31], s[36:37], 0xb8
	v_mov_b32_e32 v147, v151
	v_mov_b32_e32 v153, v151
	v_mov_b32_e32 v149, v151
	s_cmp_eq_u32 s15, 1
	s_mov_b32 s60, 0
	v_lshl_add_u64 v[8:9], s[10:11], 0, v[150:151]
	v_lshl_add_u64 v[6:7], s[10:11], 0, v[146:147]
	v_lshl_add_u64 v[2:3], s[12:13], 0, v[152:153]
	s_cselect_b64 s[24:25], -1, 0
	s_cmp_lg_u32 s15, 1
	v_lshl_add_u64 v[4:5], s[12:13], 0, v[148:149]
	s_cbranch_scc1 .LBB0_695
	s_barrier

.LBB0_796:
	s_cmp_lt_i32 s84, 12
	s_cselect_b64 s[4:5], -1, 0
	s_cmp_gt_i32 s85, 11
	s_cselect_b64 s[6:7], -1, 0
	s_and_b64 s[4:5], s[4:5], s[6:7]
	s_andn2_b64 vcc, exec, s[4:5]
	s_cbranch_vccnz .LBB0_867
	v_readfirstlane_b32 s98, v0
	s_nop 3
	s_bitcmp1_b32 s98, 8
	s_cbranch_scc0 .Lsprio_skip_12
	s_setprio 1
.Lsprio_skip_12:
	s_mov_b64 s[6:7], s[70:71]
	s_mov_b64 s[8:9], s[70:71]
	s_mov_b64 s[4:5], s[70:71]
	s_cmpk_gt_i32 s2, 0xaff
	v_readfirstlane_b32 s13, v0
	s_cbranch_scc1 .LBB0_813
	s_load_dwordx2 s[10:11], s[6:7], 0xb8
	s_load_dwordx2 s[14:15], s[8:9], 0xb8
	v_lshrrev_b32_e32 v2, 5, v0
	v_lshrrev_b32_e32 v4, 1, v0
	v_and_b32_e32 v2, 4, v2
	v_bfe_u32 v3, v0, 2, 2
	v_and_b32_e32 v13, 24, v4
	s_waitcnt lgkmcnt(0)
	s_add_u32 s40, s10, 0x18000000
	v_or3_b32 v2, v2, v3, v13
	v_lshlrev_b32_e32 v3, 4, v0
	s_addc_u32 s41, s11, 0
	v_or_b32_e32 v10, 0x2000, v3
	s_add_u32 s42, s14, 0x5000000
	v_lshrrev_b32_e32 v4, 7, v10
	s_movk_i32 s6, 0x60
	s_addc_u32 s43, s15, 0
	v_and_or_b32 v5, v4, s6, v2
	v_bfe_u32 v14, v0, 2, 4
	s_movk_i32 s6, 0x70
	s_ashr_i32 s45, s2, 31
	v_and_or_b32 v4, v4, s6, v14
	s_lshr_b32 s6, s45, 29
	s_add_i32 s6, s2, s6
	s_lshr_b32 s3, s13, 6
	s_ashr_i32 s7, s6, 3
	s_and_b32 s6, s6, -8
	s_lshr_b32 s14, s13, 8
	s_lshl_b32 s44, s3, 10
	s_sub_i32 s6, s2, s6
	s_cmp_lt_i32 s6, 0
	s_movk_i32 s46, 0x161
	s_cselect_b32 s8, s46, 0x160
	s_mul_i32 s6, s6, s8
	s_add_i32 s6, s6, s7
	s_mul_hi_i32 s7, s6, 0x2e8ba2e9
	s_lshr_b32 s8, s7, 31
	s_ashr_i32 s7, s7, 6
	s_add_i32 s7, s7, s8
	s_lshl_b32 s8, s7, 3
	s_mulk_i32 s7, 0x160
	s_sub_i32 s6, s6, s7
	s_sext_i32_i16 s7, s6
	s_bfe_u32 s7, s7, 0x3001c
	s_add_i32 s7, s6, s7
	s_sext_i32_i16 s9, s7
	s_and_b32 s7, s7, 0xfff8
	s_sub_i32 s6, s6, s7
	s_sext_i32_i16 s6, s6
	v_and_b32_e32 v6, 32, v0
	s_lshr_b32 s12, s9, 3
	s_add_i32 s30, s8, s6
	v_bitop3_b32 v11, v3, v6, 48 bitop3:0x6c
	v_and_b32_e32 v12, 64, v0
	s_ashr_i32 s31, s30, 31
	s_bfe_i64 s[8:9], s[12:13], 0x100000
	v_or_b32_e32 v3, v11, v12
	s_lshl_b64 s[6:7], s[30:31], 20
	s_lshl_b64 s[8:9], s[8:9], 20
	v_lshl_or_b32 v132, v4, 12, v3
	v_lshrrev_b32_e32 v4, 3, v0
	s_add_u32 s36, s42, s8
	v_and_or_b32 v2, v4, 32, v2
	s_addc_u32 s37, s43, s9
	s_add_i32 s31, s44, 0
	v_lshl_or_b32 v134, v2, 12, v3
	s_add_i32 m0, s31, 0x10000
	v_lshl_or_b32 v130, v5, 12, v3
	global_load_lds_dwordx4 v134, s[36:37]
	s_add_i32 m0, s31, 0x12000
	s_add_u32 s8, s36, 0x80000
	global_load_lds_dwordx4 v130, s[36:37]
	s_addc_u32 s9, s37, 0
	s_add_i32 m0, s31, 0x14000
	v_and_or_b32 v2, v4, 48, v14
	global_load_lds_dwordx4 v134, s[8:9]
	s_add_i32 m0, s31, 0x16000
	s_add_u32 s34, s40, s6
	s_addc_u32 s35, s41, s7
	s_add_i32 s47, s31, 0x2000
	v_lshl_or_b32 v136, v2, 12, v3
	global_load_lds_dwordx4 v130, s[8:9]
	s_mov_b32 m0, s31
	s_add_u32 s6, s34, 0x80000
	global_load_lds_dwordx4 v136, s[34:35]
	s_mov_b32 m0, s47
	s_addc_u32 s7, s35, 0
	s_add_i32 s48, s31, 0x4000
	global_load_lds_dwordx4 v132, s[34:35]
	s_mov_b32 m0, s48
	s_add_i32 s49, s31, 0x6000
	global_load_lds_dwordx4 v136, s[6:7]
	s_mov_b32 m0, s49
	s_load_dwordx2 s[4:5], s[4:5], 0xb8
	global_load_lds_dwordx4 v132, s[6:7]
	v_mov_b32_e32 v135, 0
	v_mov_b32_e32 v131, v135
	v_mov_b32_e32 v137, v135
	v_mov_b32_e32 v133, v135
	s_cmp_eq_u32 s14, 1
	s_mov_b32 s50, 0
	v_lshl_add_u64 v[8:9], s[36:37], 0, v[134:135]
	v_lshl_add_u64 v[6:7], s[36:37], 0, v[130:131]
	v_lshl_add_u64 v[2:3], s[34:35], 0, v[136:137]
	s_cselect_b64 s[6:7], -1, 0
	s_cmp_lg_u32 s14, 1
	v_lshl_add_u64 v[4:5], s[34:35], 0, v[132:133]
	s_cbranch_scc1 .LBB0_800
	s_barrier

.LBB0_867:
	s_cmp_lt_i32 s84, 13
	s_cselect_b64 s[4:5], -1, 0
	s_cmp_gt_i32 s85, 12
	s_cselect_b64 s[6:7], -1, 0
	s_and_b64 s[4:5], s[4:5], s[6:7]
	s_andn2_b64 vcc, exec, s[4:5]
	s_cbranch_vccnz .LBB0_974
	v_readfirstlane_b32 s98, v0
	s_nop 3
	s_bitcmp1_b32 s98, 8
	s_cbranch_scc0 .Lsprio_skip_13
	s_setprio 1
.Lsprio_skip_13:
	s_and_b32 s3, s2, 7
	s_ashr_i32 s14, s33, 6
	s_mul_i32 s56, s14, s3
	s_ashr_i32 s3, s2, 6
	s_add_i32 s56, s56, s3
	s_mov_b64 s[8:9], s[70:71]
	s_mov_b64 s[26:27], s[70:71]
	s_mov_b64 s[4:5], s[70:71]
	s_mov_b64 s[6:7], s[70:71]
	s_mov_b64 s[10:11], s[70:71]
	s_mov_b64 s[12:13], s[70:71]
	s_mov_b64 s[22:23], s[70:71]
	s_mov_b64 s[24:25], s[70:71]
	s_mov_b64 s[28:29], s[70:71]
	s_mov_b64 s[30:31], s[70:71]
	s_mov_b64 s[34:35], s[70:71]
	s_mov_b64 s[38:39], s[70:71]
	s_mov_b64 s[40:41], s[70:71]
	s_mov_b64 s[42:43], s[70:71]
	s_cmp_gt_i32 s56, 63
	v_readfirstlane_b32 s14, v0
	s_cbranch_scc1 .LBB0_920
	s_load_dwordx2 s[8:9], s[8:9], 0xb8
	s_nop 0
	s_load_dwordx2 s[26:27], s[26:27], 0xb8
	v_lshrrev_b32_e32 v2, 5, v0
	v_lshrrev_b32_e32 v4, 1, v0
	v_and_b32_e32 v2, 4, v2
	v_bfe_u32 v3, v0, 2, 2
	v_and_b32_e32 v4, 24, v4
	v_lshlrev_b32_e32 v216, 4, v0
	v_or3_b32 v2, v2, v3, v4
	v_bfe_u32 v3, v0, 3, 25
	v_and_b32_e32 v5, 32, v0
	s_waitcnt lgkmcnt(0)
	s_add_u32 s57, s8, 0x20000000
	v_or_b32_e32 v3, 64, v3
	s_movk_i32 s8, 0x60
	v_bitop3_b32 v10, v216, v5, 48 bitop3:0x6c
	v_and_b32_e32 v11, 64, v0
	v_and_or_b32 v4, v3, s8, v2
	v_or_b32_e32 v5, v10, v11
	v_mul_u32_u24_e32 v4, 0x1600, v4
	v_lshrrev_b32_e32 v5, 1, v5
	v_or_b32_e32 v4, v4, v5
	v_lshlrev_b32_e32 v146, 1, v4
	v_bfe_u32 v4, v0, 2, 4
	s_movk_i32 s8, 0x70
	v_and_or_b32 v3, v3, s8, v4
	s_addc_u32 s60, s9, 0
	s_lshr_b32 s18, s14, 6
	s_bfe_u32 s16, s2, 0x30003
	v_mul_u32_u24_e32 v12, 0x1600, v3
	s_lshr_b32 s17, s14, 8
	s_lshl_b32 s3, s18, 10
	v_or_b32_e32 v3, v12, v5
	s_mul_i32 s15, s16, 0x2c0000
	v_lshlrev_b32_e32 v148, 1, v3
	v_lshrrev_b32_e32 v3, 3, v0
	s_add_u32 s20, s26, s15
	v_and_or_b32 v2, v3, 32, v2
	s_addc_u32 s21, s27, 0
	v_mul_u32_u24_e32 v2, 0x1600, v2
	s_add_u32 s8, s20, 0xea00000
	v_or_b32_e32 v2, v2, v5
	s_addc_u32 s9, s21, 0
	s_add_i32 s61, s3, 0
	v_lshlrev_b32_e32 v150, 1, v2
	s_add_i32 m0, s61, 0x10000
	v_and_or_b32 v2, v3, 48, v4
	global_load_lds_dwordx4 v150, s[8:9]
	s_add_i32 m0, s61, 0x12000
	s_add_u32 s20, s20, 0xeb60000
	global_load_lds_dwordx4 v146, s[8:9]
	s_addc_u32 s21, s21, 0
	s_add_i32 m0, s61, 0x14000
	s_mul_i32 s36, s56, 0x2c0000
	global_load_lds_dwordx4 v150, s[20:21]
	s_add_i32 m0, s61, 0x16000
	v_mul_u32_u24_e32 v13, 0x1600, v2
	s_mul_hi_i32 s19, s56, 0x2c0000
	s_add_u32 s36, s57, s36
	v_or_b32_e32 v2, v5, v13
	s_addc_u32 s37, s60, s19
	s_add_i32 s62, s61, 0x2000
	v_lshlrev_b32_e32 v152, 1, v2
	global_load_lds_dwordx4 v146, s[20:21]
	s_mov_b32 m0, s61
	s_add_u32 s20, s36, 0x160000
	global_load_lds_dwordx4 v152, s[36:37]
	s_mov_b32 m0, s62
	s_addc_u32 s21, s37, 0
	s_add_i32 s63, s61, 0x4000
	global_load_lds_dwordx4 v148, s[36:37]
	s_mov_b32 m0, s63
	s_add_i32 s64, s61, 0x6000
	global_load_lds_dwordx4 v152, s[20:21]
	s_mov_b32 m0, s64
	v_mov_b32_e32 v151, 0
	global_load_lds_dwordx4 v148, s[20:21]
	s_load_dwordx2 s[52:53], s[4:5], 0xb0
	s_load_dwordx2 s[48:49], s[6:7], 0xb0
	s_load_dwordx2 s[54:55], s[10:11], 0xb8
	s_nop 0
	s_load_dwordx2 s[6:7], s[12:13], 0xb8
	s_load_dwordx2 s[4:5], s[22:23], 0xb8
	s_load_dwordx2 s[10:11], s[24:25], 0xb8
	s_load_dwordx2 s[50:51], s[28:29], 0xb8
	s_load_dwordx2 s[46:47], s[30:31], 0xb8
	s_load_dwordx2 s[44:45], s[34:35], 0xb8
	s_nop 0
	s_load_dwordx2 s[34:35], s[38:39], 0xb8
	s_load_dwordx2 s[30:31], s[40:41], 0xb8
	s_load_dwordx2 s[28:29], s[42:43], 0xb8
	v_mov_b32_e32 v147, v151
	v_mov_b32_e32 v153, v151
	v_mov_b32_e32 v149, v151
	s_cmp_eq_u32 s17, 1
	s_mov_b32 s65, 0
	v_lshl_add_u64 v[8:9], s[8:9], 0, v[150:151]
	v_lshl_add_u64 v[6:7], s[8:9], 0, v[146:147]
	v_lshl_add_u64 v[2:3], s[36:37], 0, v[152:153]
	s_cselect_b64 s[12:13], -1, 0
	s_cmp_lg_u32 s17, 1
	v_lshl_add_u64 v[4:5], s[36:37], 0, v[148:149]
	s_cbranch_scc1 .LBB0_871
	s_barrier

.LBB0_974:
	s_cmp_lt_i32 s84, 15
	s_cselect_b64 s[4:5], -1, 0
	s_cmp_gt_i32 s85, 14
	s_cselect_b64 s[6:7], -1, 0
	s_and_b64 s[4:5], s[4:5], s[6:7]
	s_andn2_b64 vcc, exec, s[4:5]
	s_cbranch_vccnz .LBB0_1015
	v_readfirstlane_b32 s98, v0
	s_nop 3
	s_bitcmp1_b32 s98, 8
	s_cbranch_scc0 .Lsprio_skip_15
	s_setprio 1
.Lsprio_skip_15:
	s_cmpk_lt_i32 s2, 0xc0
	s_mov_b64 s[8:9], s[70:71]
	s_mov_b64 s[28:29], s[70:71]
	s_mov_b64 s[4:5], s[70:71]
	s_mov_b64 s[6:7], s[70:71]
	s_mov_b64 s[12:13], s[70:71]
	s_mov_b64 s[22:23], s[70:71]
	s_mov_b64 s[24:25], s[70:71]
	s_mov_b64 s[26:27], s[70:71]
	s_cselect_b64 s[30:31], -1, 0
	s_cmpk_gt_i32 s2, 0xbf
	v_readfirstlane_b32 s3, v0
	s_cbranch_scc1 .LBB0_977
	s_ashr_i32 s10, s2, 31
	s_lshr_b32 s10, s10, 29
	s_add_i32 s10, s2, s10
	s_ashr_i32 s11, s10, 3
	s_and_b32 s10, s10, -8
	s_sub_i32 s10, s2, s10
	s_cmp_lt_i32 s10, 0
	s_cselect_b32 s14, 25, 24
	s_mul_i32 s10, s10, s14
	s_add_i32 s10, s10, s11
	s_mul_hi_i32 s11, s10, 0x2aaaaaab
	s_lshr_b32 s14, s11, 31
	s_ashr_i32 s11, s11, 2
	s_add_i32 s11, s11, s14
	s_lshl_b32 s14, s11, 3
	s_mul_i32 s11, s11, 24
	s_sub_i32 s10, s10, s11
	s_bfe_i32 s11, s10, 0x80000
	s_bfe_u32 s11, s11, 0x3000c
	s_add_i32 s11, s10, s11
	s_bfe_i32 s15, s11, 0x80000
	s_and_b32 s11, s11, 0xf8
	s_sub_i32 s10, s10, s11
	s_sext_i32_i16 s15, s15
	s_sext_i32_i8 s10, s10
	s_add_i32 s50, s14, s10
	s_ashr_i32 s10, s15, 3

.LBB0_1015:
	s_cmp_lt_i32 s84, 16
	s_cselect_b64 s[4:5], -1, 0
	s_cmp_gt_i32 s85, 15
	s_cselect_b64 s[6:7], -1, 0
	s_and_b64 s[4:5], s[4:5], s[6:7]
	s_andn2_b64 vcc, exec, s[4:5]
	s_cbranch_vccnz .LBB0_1086
	v_readfirstlane_b32 s98, v0
	s_nop 3
	s_bitcmp1_b32 s98, 8
	s_cbranch_scc0 .Lsprio_skip_16
	s_setprio 1
.Lsprio_skip_16:
	s_mov_b64 s[6:7], s[70:71]
	s_mov_b64 s[8:9], s[70:71]
	s_mov_b64 s[4:5], s[70:71]
	s_cmpk_gt_i32 s2, 0xaff
	v_readfirstlane_b32 s13, v0
	s_cbranch_scc1 .LBB0_1032
	s_load_dwordx2 s[10:11], s[6:7], 0xb8
	s_load_dwordx2 s[14:15], s[8:9], 0xb8
	v_lshrrev_b32_e32 v2, 5, v0
	v_lshrrev_b32_e32 v4, 1, v0
	v_and_b32_e32 v2, 4, v2
	v_bfe_u32 v3, v0, 2, 2
	v_and_b32_e32 v13, 24, v4
	s_waitcnt lgkmcnt(0)
	s_add_u32 s40, s10, 0x18000000
	v_or3_b32 v2, v2, v3, v13
	v_lshlrev_b32_e32 v3, 4, v0
	s_addc_u32 s41, s11, 0
	v_or_b32_e32 v10, 0x2000, v3
	s_add_u32 s42, s14, 0x7c00000
	v_lshrrev_b32_e32 v4, 7, v10
	s_movk_i32 s6, 0x60
	s_addc_u32 s43, s15, 0
	v_and_or_b32 v5, v4, s6, v2
	v_bfe_u32 v14, v0, 2, 4
	s_movk_i32 s6, 0x70
	s_ashr_i32 s45, s2, 31
	v_and_or_b32 v4, v4, s6, v14
	s_lshr_b32 s6, s45, 29
	s_add_i32 s6, s2, s6
	s_lshr_b32 s3, s13, 6
	s_ashr_i32 s7, s6, 3
	s_and_b32 s6, s6, -8
	s_lshr_b32 s14, s13, 8
	s_lshl_b32 s44, s3, 10
	s_sub_i32 s6, s2, s6
	s_cmp_lt_i32 s6, 0
	s_movk_i32 s46, 0x161
	s_cselect_b32 s8, s46, 0x160
	s_mul_i32 s6, s6, s8
	s_add_i32 s6, s6, s7
	s_mul_hi_i32 s7, s6, 0x2e8ba2e9
	s_lshr_b32 s8, s7, 31
	s_ashr_i32 s7, s7, 6
	s_add_i32 s7, s7, s8
	s_lshl_b32 s8, s7, 3
	s_mulk_i32 s7, 0x160
	s_sub_i32 s6, s6, s7
	s_sext_i32_i16 s7, s6
	s_bfe_u32 s7, s7, 0x3001c
	s_add_i32 s7, s6, s7
	s_sext_i32_i16 s9, s7
	s_and_b32 s7, s7, 0xfff8
	s_sub_i32 s6, s6, s7
	s_sext_i32_i16 s6, s6
	v_and_b32_e32 v6, 32, v0
	s_lshr_b32 s12, s9, 3
	s_add_i32 s30, s8, s6
	v_bitop3_b32 v11, v3, v6, 48 bitop3:0x6c
	v_and_b32_e32 v12, 64, v0
	s_ashr_i32 s31, s30, 31
	s_bfe_i64 s[8:9], s[12:13], 0x100000
	v_or_b32_e32 v3, v11, v12
	s_lshl_b64 s[6:7], s[30:31], 20
	s_lshl_b64 s[8:9], s[8:9], 20
	v_lshl_or_b32 v132, v4, 12, v3
	v_lshrrev_b32_e32 v4, 3, v0
	s_add_u32 s36, s42, s8
	v_and_or_b32 v2, v4, 32, v2
	s_addc_u32 s37, s43, s9
	s_add_i32 s31, s44, 0
	v_lshl_or_b32 v134, v2, 12, v3
	s_add_i32 m0, s31, 0x10000
	v_lshl_or_b32 v130, v5, 12, v3
	global_load_lds_dwordx4 v134, s[36:37]
	s_add_i32 m0, s31, 0x12000
	s_add_u32 s8, s36, 0x80000
	global_load_lds_dwordx4 v130, s[36:37]
	s_addc_u32 s9, s37, 0
	s_add_i32 m0, s31, 0x14000
	v_and_or_b32 v2, v4, 48, v14
	global_load_lds_dwordx4 v134, s[8:9]
	s_add_i32 m0, s31, 0x16000
	s_add_u32 s34, s40, s6
	s_addc_u32 s35, s41, s7
	s_add_i32 s47, s31, 0x2000
	v_lshl_or_b32 v136, v2, 12, v3
	global_load_lds_dwordx4 v130, s[8:9]
	s_mov_b32 m0, s31
	s_add_u32 s6, s34, 0x80000
	global_load_lds_dwordx4 v136, s[34:35]
	s_mov_b32 m0, s47
	s_addc_u32 s7, s35, 0
	s_add_i32 s48, s31, 0x4000
	global_load_lds_dwordx4 v132, s[34:35]
	s_mov_b32 m0, s48
	s_add_i32 s49, s31, 0x6000
	global_load_lds_dwordx4 v136, s[6:7]
	s_mov_b32 m0, s49
	s_load_dwordx2 s[4:5], s[4:5], 0xb8
	global_load_lds_dwordx4 v132, s[6:7]
	v_mov_b32_e32 v135, 0
	v_mov_b32_e32 v131, v135
	v_mov_b32_e32 v137, v135
	v_mov_b32_e32 v133, v135
	s_cmp_eq_u32 s14, 1
	s_mov_b32 s50, 0
	v_lshl_add_u64 v[8:9], s[36:37], 0, v[134:135]
	v_lshl_add_u64 v[6:7], s[36:37], 0, v[130:131]
	v_lshl_add_u64 v[2:3], s[34:35], 0, v[136:137]
	s_cselect_b64 s[6:7], -1, 0
	s_cmp_lg_u32 s14, 1
	v_lshl_add_u64 v[4:5], s[34:35], 0, v[132:133]
	s_cbranch_scc1 .LBB0_1019
	s_barrier

.LBB0_1086:
	s_cmp_lt_i32 s84, 17
	s_cselect_b64 s[4:5], -1, 0
	s_cmp_gt_i32 s85, 16
	s_cselect_b64 s[6:7], -1, 0
	s_and_b64 s[4:5], s[4:5], s[6:7]
	s_andn2_b64 vcc, exec, s[4:5]
	s_cbranch_vccnz .LBB0_1193
	v_readfirstlane_b32 s98, v0
	s_nop 3
	s_bitcmp1_b32 s98, 8
	s_cbranch_scc0 .Lsprio_skip_17
	s_setprio 1
.Lsprio_skip_17:
	s_and_b32 s3, s2, 7
	s_ashr_i32 s14, s33, 6
	s_mul_i32 s48, s14, s3
	s_ashr_i32 s3, s2, 6
	s_add_i32 s48, s48, s3
	s_mov_b64 s[8:9], s[70:71]
	s_mov_b64 s[34:35], s[70:71]
	s_mov_b64 s[4:5], s[70:71]
	s_mov_b64 s[6:7], s[70:71]
	s_mov_b64 s[10:11], s[70:71]
	s_mov_b64 s[12:13], s[70:71]
	s_mov_b64 s[22:23], s[70:71]
	s_mov_b64 s[24:25], s[70:71]
	s_mov_b64 s[26:27], s[70:71]
	s_mov_b64 s[28:29], s[70:71]
	s_mov_b64 s[30:31], s[70:71]
	s_cmp_gt_i32 s48, 63
	v_readfirstlane_b32 s14, v0
	s_cbranch_scc1 .LBB0_1139
	v_lshrrev_b32_e32 v2, 5, v0
	v_lshrrev_b32_e32 v4, 1, v0
	v_and_b32_e32 v2, 4, v2
	v_bfe_u32 v3, v0, 2, 2
	v_and_b32_e32 v4, 24, v4
	v_lshlrev_b32_e32 v210, 4, v0
	v_or3_b32 v2, v2, v3, v4
	v_bfe_u32 v3, v0, 3, 25
	s_waitcnt lgkmcnt(0)
	v_and_b32_e32 v5, 32, v0
	s_load_dwordx2 s[16:17], s[8:9], 0xb8
	s_load_dwordx2 s[18:19], s[34:35], 0xb8
	v_or_b32_e32 v3, 64, v3
	s_movk_i32 s8, 0x60
	v_bitop3_b32 v10, v210, v5, 48 bitop3:0x6c
	v_and_b32_e32 v11, 64, v0
	v_and_or_b32 v4, v3, s8, v2
	v_or_b32_e32 v5, v10, v11
	v_mul_u32_u24_e32 v4, 0x1600, v4
	v_lshrrev_b32_e32 v5, 1, v5
	v_or_b32_e32 v4, v4, v5
	v_lshlrev_b32_e32 v146, 1, v4
	v_bfe_u32 v4, v0, 2, 4
	s_movk_i32 s8, 0x70
	s_waitcnt lgkmcnt(0)
	s_add_u32 s49, s16, 0x20000000
	v_and_or_b32 v3, v3, s8, v4
	s_addc_u32 s50, s17, 0
	s_lshr_b32 s17, s14, 6
	s_bfe_u32 s15, s2, 0x30003
	v_mul_u32_u24_e32 v12, 0x1600, v3
	s_lshr_b32 s16, s14, 8
	s_lshl_b32 s3, s17, 10
	v_or_b32_e32 v3, v12, v5
	s_mul_i32 s8, s15, 0x2c0000
	v_lshlrev_b32_e32 v148, 1, v3
	v_lshrrev_b32_e32 v3, 3, v0
	s_add_u32 s18, s18, s8
	v_and_or_b32 v2, v3, 32, v2
	s_addc_u32 s19, s19, 0
	v_mul_u32_u24_e32 v2, 0x1600, v2
	s_add_u32 s8, s18, 0x10000000
	v_or_b32_e32 v2, v2, v5
	s_addc_u32 s9, s19, 0
	s_add_i32 s51, s3, 0
	v_lshlrev_b32_e32 v150, 1, v2
	s_add_i32 m0, s51, 0x10000
	v_and_or_b32 v2, v3, 48, v4
	global_load_lds_dwordx4 v150, s[8:9]
	s_add_i32 m0, s51, 0x12000
	s_add_u32 s18, s18, 0x10160000
	global_load_lds_dwordx4 v146, s[8:9]
	s_addc_u32 s19, s19, 0
	s_add_i32 m0, s51, 0x14000
	s_mul_i32 s21, s48, 0x2c0000
	global_load_lds_dwordx4 v150, s[18:19]
	s_add_i32 m0, s51, 0x16000
	v_mul_u32_u24_e32 v13, 0x1600, v2
	s_mul_hi_i32 s20, s48, 0x2c0000
	s_add_u32 s34, s49, s21
	v_or_b32_e32 v2, v5, v13
	s_addc_u32 s35, s50, s20
	s_add_i32 s52, s51, 0x2000
	v_lshlrev_b32_e32 v152, 1, v2
	global_load_lds_dwordx4 v146, s[18:19]
	s_mov_b32 m0, s51
	s_add_u32 s18, s34, 0x160000
	global_load_lds_dwordx4 v152, s[34:35]
	s_mov_b32 m0, s52
	s_addc_u32 s19, s35, 0
	s_add_i32 s53, s51, 0x4000
	global_load_lds_dwordx4 v148, s[34:35]
	s_mov_b32 m0, s53
	s_add_i32 s54, s51, 0x6000
	global_load_lds_dwordx4 v152, s[18:19]
	s_mov_b32 m0, s54
	v_mov_b32_e32 v151, 0
	global_load_lds_dwordx4 v148, s[18:19]
	s_load_dwordx2 s[40:41], s[4:5], 0xb0
	s_load_dwordx2 s[36:37], s[6:7], 0xb0
	s_load_dwordx2 s[42:43], s[10:11], 0xb8
	s_nop 0
	s_load_dwordx2 s[6:7], s[12:13], 0xb8
	s_load_dwordx2 s[4:5], s[22:23], 0xb8
	s_load_dwordx2 s[10:11], s[24:25], 0xb8
	s_load_dwordx2 s[38:39], s[26:27], 0xb8
	s_nop 0
	s_load_dwordx2 s[28:29], s[28:29], 0xb8
	s_nop 0
	s_load_dwordx2 s[26:27], s[30:31], 0xb8
	v_mov_b32_e32 v147, v151
	v_mov_b32_e32 v153, v151
	v_mov_b32_e32 v149, v151
	s_cmp_eq_u32 s16, 1
	s_mov_b32 s55, 0
	v_lshl_add_u64 v[8:9], s[8:9], 0, v[150:151]
	v_lshl_add_u64 v[6:7], s[8:9], 0, v[146:147]
	v_lshl_add_u64 v[2:3], s[34:35], 0, v[152:153]
	s_cselect_b64 s[12:13], -1, 0
	s_cmp_lg_u32 s16, 1
	v_lshl_add_u64 v[4:5], s[34:35], 0, v[148:149]
	s_cbranch_scc1 .LBB0_1090
	s_barrier

.LBB0_1193:
	s_cmp_lt_i32 s84, 19
	s_cselect_b64 s[4:5], -1, 0
	s_cmp_gt_i32 s85, 18
	s_cselect_b64 s[6:7], -1, 0
	s_and_b64 s[4:5], s[4:5], s[6:7]
	s_andn2_b64 vcc, exec, s[4:5]
	s_cbranch_vccnz .LBB0_1326
	v_readfirstlane_b32 s98, v0
	s_nop 3
	s_bitcmp1_b32 s98, 8
	s_cbranch_scc0 .Lsprio_skip_19
	s_setprio 1
.Lsprio_skip_19:
	s_mov_b64 s[4:5], s[70:71]
	s_load_dwordx2 s[12:13], s[4:5], 0xb8
	s_mov_b64 s[4:5], s[70:71]
	s_load_dwordx2 s[22:23], s[4:5], 0xb8
	s_mov_b64 s[4:5], s[70:71]
	s_mov_b64 s[6:7], s[70:71]
	s_load_dwordx2 s[4:5], s[4:5], 0xb8
	s_load_dwordx2 s[8:9], s[6:7], 0x90
	s_mov_b64 s[6:7], s[70:71]
	s_load_dwordx2 s[6:7], s[6:7], 0xb8
	s_cmpk_lt_i32 s2, 0x80
	s_cselect_b64 s[24:25], -1, 0
	s_cmpk_gt_i32 s2, 0x7f
	v_readfirstlane_b32 s3, v0
	s_cbranch_scc1 .LBB0_1200
	s_ashr_i32 s10, s2, 31
	s_lshr_b32 s10, s10, 29
	s_add_i32 s14, s2, s10
	s_and_b32 s10, s14, -8
	s_sub_i32 s15, s2, s10
	s_cmp_gt_i32 s15, -1
	s_cbranch_scc0 .LBB0_1197
	s_lshl_b32 s16, s15, 4
	s_cbranch_execz .LBB0_1198
	s_branch .LBB0_1199

.LBB0_1326:
	s_cmp_lt_i32 s84, 20
	s_cselect_b64 s[4:5], -1, 0
	s_cmp_gt_i32 s85, 19
	s_cselect_b64 s[6:7], -1, 0
	s_and_b64 s[4:5], s[4:5], s[6:7]
	s_andn2_b64 vcc, exec, s[4:5]
	s_cbranch_vccnz .LBB0_1401
	v_readfirstlane_b32 s98, v0
	s_nop 3
	s_bitcmp1_b32 s98, 8
	s_cbranch_scc0 .Lsprio_skip_20
	s_setprio 1
.Lsprio_skip_20:
	s_mov_b64 s[6:7], s[70:71]
	s_mov_b64 s[22:23], s[70:71]
	s_mov_b64 s[4:5], s[70:71]
	s_mov_b64 s[8:9], s[70:71]
	s_mov_b64 s[10:11], s[70:71]
	s_mov_b64 s[12:13], s[70:71]
	s_cmpk_gt_i32 s2, 0x2ff
	v_readfirstlane_b32 s3, v0
	s_cbranch_scc1 .LBB0_1347
	s_load_dwordx2 s[14:15], s[6:7], 0xb8
	s_load_dwordx2 s[16:17], s[22:23], 0xb8
	v_lshrrev_b32_e32 v2, 5, v0
	v_and_b32_e32 v3, 4, v2
	v_lshrrev_b32_e32 v2, 1, v0
	s_waitcnt lgkmcnt(0)
	s_add_u32 s42, s14, 0x2c000000
	v_bfe_u32 v4, v0, 2, 2
	v_and_b32_e32 v2, 24, v2
	v_lshlrev_b32_e32 v5, 4, v0
	s_addc_u32 s43, s15, 0
	v_or3_b32 v4, v3, v4, v2
	v_or_b32_e32 v3, 0x2000, v5
	s_add_u32 s44, s16, 0x17500000
	v_lshrrev_b32_e32 v6, 7, v3
	s_movk_i32 s6, 0x60
	s_addc_u32 s45, s17, 0
	v_and_or_b32 v7, v6, s6, v4
	v_bfe_u32 v14, v0, 2, 4
	s_movk_i32 s6, 0x70
	s_ashr_i32 s47, s2, 31
	v_and_or_b32 v6, v6, s6, v14
	s_lshr_b32 s6, s47, 29
	s_add_i32 s6, s2, s6
	s_lshr_b32 s15, s3, 6
	s_ashr_i32 s7, s6, 3
	s_and_b32 s6, s6, -8
	s_lshr_b32 s14, s3, 8
	s_lshl_b32 s46, s15, 10
	s_sub_i32 s6, s2, s6
	s_cmp_lt_i32 s6, 0
	s_movk_i32 s48, 0x61
	s_cselect_b32 s16, s48, 0x60
	s_mul_i32 s6, s6, s16
	s_add_i32 s6, s6, s7
	s_mul_hi_i32 s7, s6, 0x2aaaaaab
	s_lshr_b32 s16, s7, 31
	s_ashr_i32 s7, s7, 4
	s_add_i32 s7, s7, s16
	s_lshl_b32 s16, s7, 3
	s_mulk_i32 s7, 0x60
	s_sub_i32 s6, s6, s7
	s_bfe_i32 s7, s6, 0x80000
	s_bfe_u32 s7, s7, 0x3000c
	s_add_i32 s7, s6, s7
	s_bfe_i32 s17, s7, 0x80000
	s_and_b32 s7, s7, 0xf8
	s_sub_i32 s6, s6, s7
	s_sext_i32_i16 s17, s17
	s_sext_i32_i8 s6, s6
	v_and_b32_e32 v8, 32, v0
	s_lshr_b32 s24, s17, 3
	s_add_i32 s6, s16, s6
	v_bitop3_b32 v12, v5, v8, 48 bitop3:0x6c
	v_and_b32_e32 v13, 64, v0
	s_ashr_i32 s7, s6, 31
	s_bfe_i64 s[18:19], s[24:25], 0x100000
	v_or_b32_e32 v5, v12, v13
	s_lshl_b64 s[16:17], s[6:7], 18
	s_lshl_b64 s[18:19], s[18:19], 18
	v_lshl_or_b32 v132, v6, 10, v5
	v_lshrrev_b32_e32 v6, 3, v0
	s_add_u32 s38, s44, s18
	v_and_or_b32 v4, v6, 32, v4
	s_addc_u32 s39, s45, s19
	s_add_i32 s49, s46, 0
	v_lshl_or_b32 v134, v4, 10, v5
	s_add_i32 m0, s49, 0x10000
	v_lshl_or_b32 v130, v7, 10, v5
	global_load_lds_dwordx4 v134, s[38:39]
	s_add_i32 m0, s49, 0x12000
	s_add_u32 s18, s38, 0x20000
	global_load_lds_dwordx4 v130, s[38:39]
	s_addc_u32 s19, s39, 0
	s_add_i32 m0, s49, 0x14000
	v_and_or_b32 v4, v6, 48, v14
	global_load_lds_dwordx4 v134, s[18:19]
	s_add_i32 m0, s49, 0x16000
	s_add_u32 s36, s42, s16
	s_addc_u32 s37, s43, s17
	s_add_i32 s50, s49, 0x2000
	v_lshl_or_b32 v136, v4, 10, v5
	global_load_lds_dwordx4 v130, s[18:19]
	s_mov_b32 m0, s49
	s_add_u32 s16, s36, 0x20000
	global_load_lds_dwordx4 v136, s[36:37]
	s_mov_b32 m0, s50
	s_addc_u32 s17, s37, 0
	s_add_i32 s51, s49, 0x4000
	global_load_lds_dwordx4 v132, s[36:37]
	s_mov_b32 m0, s51
	s_add_i32 s52, s49, 0x6000
	global_load_lds_dwordx4 v136, s[16:17]
	s_mov_b32 m0, s52
	v_mov_b32_e32 v139, 0
	global_load_lds_dwordx4 v132, s[16:17]
	s_load_dwordx2 s[28:29], s[4:5], 0xb8
	s_load_dwordx2 s[22:23], s[8:9], 0xb8
	s_load_dwordx2 s[26:27], s[10:11], 0xb8
	s_nop 0
	s_load_dwordx2 s[4:5], s[12:13], 0xb8
	v_mov_b32_e32 v135, v139
	v_mov_b32_e32 v131, v139
	v_mov_b32_e32 v137, v139
	v_mov_b32_e32 v133, v139
	s_cmp_eq_u32 s14, 1
	s_mov_b32 s7, 0
	v_lshl_add_u64 v[10:11], s[38:39], 0, v[134:135]
	v_lshl_add_u64 v[8:9], s[38:39], 0, v[130:131]
	v_lshl_add_u64 v[4:5], s[36:37], 0, v[136:137]
	s_cselect_b64 s[8:9], -1, 0
	s_cmp_lg_u32 s14, 1
	v_lshl_add_u64 v[6:7], s[36:37], 0, v[132:133]
	s_cbranch_scc1 .LBB0_1330
	s_barrier

.LBB0_1401:
	s_cmp_lt_i32 s84, 21
	s_cselect_b64 s[4:5], -1, 0
	s_cmp_gt_i32 s85, 20
	s_cselect_b64 s[6:7], -1, 0
	s_and_b64 s[4:5], s[4:5], s[6:7]
	s_andn2_b64 vcc, exec, s[4:5]
	s_cbranch_vccnz .LBB0_1489
	s_setprio 0
	s_mov_b64 s[6:7], s[70:71]
	v_writelane_b32 v254, s94, 0
	s_mov_b64 s[8:9], s[70:71]
	s_mov_b64 s[10:11], s[70:71]
	v_writelane_b32 v254, s95, 1
	v_writelane_b32 v254, s92, 2
	s_mov_b64 s[22:23], s[70:71]
	s_cmpk_gt_i32 s72, 0x1ff
	v_writelane_b32 v254, s93, 3
	v_writelane_b32 v254, s90, 4
	v_writelane_b32 v254, s88, 5
	s_nop 1
	v_writelane_b32 v254, s89, 6
	v_writelane_b32 v254, s86, 7
	s_nop 1
	v_writelane_b32 v254, s87, 8
	v_writelane_b32 v254, s85, 9
	v_writelane_b32 v254, s84, 10
	v_writelane_b32 v254, s2, 11
	v_writelane_b32 v254, s70, 12
	s_nop 1
	v_writelane_b32 v254, s71, 13
	s_cbranch_scc1 .LBB0_1435
	v_lshrrev_b32_e32 v3, 5, v1
	v_lshlrev_b32_e32 v6, 5, v1
	v_lshlrev_b32_e32 v8, 3, v0
	v_and_b32_e32 v6, 0x180, v6
	v_lshlrev_b32_e32 v7, 9, v3
	v_and_b32_e32 v8, 8, v8
	v_or3_b32 v6, v7, v6, v8
	v_lshrrev_b32_e32 v7, 3, v0
	v_lshrrev_b32_e32 v2, 1, v1
	v_and_b32_e32 v7, 2, v7
	v_and_or_b32 v7, v2, 1, v7
	s_load_dwordx2 s[14:15], s[8:9], 0xb8
	s_load_dwordx2 s[16:17], s[6:7], 0xb8
	s_load_dwordx2 s[18:19], s[10:11], 0xb8
	s_load_dwordx2 s[12:13], s[22:23], 0xb8
	v_and_or_b32 v8, v2, 4, v7
	v_bitop3_b32 v2, v7, v2, 4 bitop3:0x72
	v_lshl_or_b32 v163, v8, 4, v6
	v_lshl_or_b32 v212, v2, 4, v6
	v_lshrrev_b32_e32 v2, 4, v1
	v_and_b32_e32 v6, 7, v0
	s_waitcnt lgkmcnt(0)
	s_add_u32 s35, s14, 0x2d400000
	v_bitop3_b32 v7, v2, v6, 4 bitop3:0x36
	v_lshrrev_b32_e32 v8, 3, v1
	v_bitop3_b32 v2, v2, v0, 7 bitop3:0x78
	s_addc_u32 s0, s15, 0
	v_lshrrev_b32_e32 v4, 2, v1
	v_lshlrev_b32_e32 v7, 3, v7
	v_lshlrev_b32_e32 v9, 6, v8
	v_lshlrev_b32_e32 v8, 11, v8
	v_lshlrev_b32_e32 v2, 3, v2
	v_writelane_b32 v254, s0, 14
	s_add_u32 s0, s18, 0x2d000000
	v_or_b32_e32 v10, v7, v9
	v_or_b32_e32 v13, v2, v9
	v_or_b32_e32 v14, v2, v8
	v_and_b32_e32 v9, 31, v0
	v_bitop3_b32 v2, v4, v6, 4 bitop3:0x6c
	v_writelane_b32 v254, s0, 15
	s_addc_u32 s0, s19, 0
	v_and_b32_e32 v12, 4, v4
	v_or_b32_e32 v11, v7, v8
	v_lshl_or_b32 v4, v2, 3, v8
	v_mul_u32_u24_e32 v2, 0xc00, v9
	v_lshlrev_b32_e32 v8, 3, v3
	v_writelane_b32 v254, s0, 16
	s_add_u32 s0, s12, 0x31400000
	v_or_b32_e32 v6, v8, v2
	v_mov_b32_e32 v2, 0
	v_writelane_b32 v254, s0, 17
	s_addc_u32 s0, s13, 0
	v_lshlrev_b32_e32 v5, 7, v0
	s_lshl_b32 s6, s59, 11
	v_lshlrev_b32_e32 v6, 1, v6
	v_mov_b32_e32 v7, v2
	v_and_b32_e32 v213, 0xf80, v5
	s_load_dwordx2 s[4:5], s[70:71], 0xb8
	v_bfe_u32 v5, v1, 1, 2
	s_add_i32 s80, s6, 0
	v_lshl_add_u64 v[6:7], s[16:17], 0, v[6:7]
	s_mov_b64 s[6:7], 0x20000000
	v_lshl_add_u64 v[164:165], v[6:7], 0, s[6:7]
	v_bitop3_b32 v6, v5, v3, v12 bitop3:0x36
	v_lshlrev_b32_e32 v214, 4, v6
	v_or_b32_e32 v6, 2, v3
	v_bitop3_b32 v6, v5, v6, v12 bitop3:0x36
	s_lshl_b32 s22, s59, 3
	s_mov_b32 s23, 0
	v_lshlrev_b32_e32 v215, 4, v6
	v_lshl_or_b32 v6, v9, 12, v8
	v_mov_b32_e32 v7, v2
	v_writelane_b32 v254, s0, 18
	s_lshr_b32 s79, s58, 7
	s_mul_i32 s3, s59, 3
	s_lshl_b64 s[24:25], s[22:23], 12
	s_add_i32 s81, s80, 0x12000
	s_lshl_b32 s0, s59, 5
	s_and_b32 s6, s58, 0xffffff00
	s_waitcnt lgkmcnt(0)
	v_lshl_add_u64 v[6:7], s[4:5], 0, v[6:7]
	s_mov_b64 s[4:5], 0x26000000
	s_cmpk_eq_i32 s6, 0x100
	v_lshl_add_u64 v[166:167], v[6:7], 0, s[4:5]
	s_mul_hi_u32 s4, s3, 0x15555556
	s_cselect_b64 s[26:27], -1, 0
	s_cmpk_lt_u32 s58, 0x100
	s_mul_i32 s4, s4, 12
	s_cselect_b64 s[28:29], -1, 0
	s_sub_i32 s18, s3, s4
	s_and_b32 s4, s3, 3
	s_lshr_b32 s5, s58, 3
	s_and_b32 s5, s5, 0x1fffffe0
	s_lshl_b32 s6, s4, 3
	s_or_b32 s22, s5, s6
	v_writelane_b32 v254, s0, 19
	s_lshl_b64 s[0:1], s[22:23], 7
	v_writelane_b32 v254, s0, 20
	s_lshl_b32 s5, s18, 4
	s_and_b32 s19, s5, 0xc0
	v_writelane_b32 v254, s1, 21
	s_lshl_b64 s[0:1], s[22:23], 12
	s_cmp_lt_u32 s4, 2
	s_cselect_b64 vcc, -1, 0
	s_add_i32 s6, s3, 1
	s_mul_hi_u32 s4, s6, 0x15555556
	s_mul_i32 s5, s4, 12
	s_and_b32 s8, s6, 3
	s_sub_i32 s7, s6, s5
	s_lshl_b32 s4, s4, 5
	s_lshl_b32 s5, s8, 3
	s_or_b32 s14, s4, s5
	s_cmp_lt_u32 s7, 8
	s_mov_b32 s15, s23
	s_cselect_b64 s[4:5], -1, 0
	s_lshl_b32 s7, s7, 4
	s_lshl_b64 s[36:37], s[14:15], 7
	s_lshl_b64 s[38:39], s[14:15], 12
	s_and_b32 s15, s7, 0xc0
	s_cmp_lt_u32 s8, 2
	s_cselect_b64 s[8:9], -1, 0
	s_add_i32 s3, s3, 2
	s_lshl_b32 s83, s6, 10
	s_mul_hi_u32 s6, s3, 0x15555556
	s_mul_i32 s7, s6, 12
	s_sub_i32 s20, s3, s7
	s_and_b32 s7, s3, 3
	s_lshl_b32 s6, s6, 5
	s_lshl_b32 s10, s7, 3
	s_or_b32 s16, s6, s10
	s_mov_b32 s17, s23
	s_lshl_b32 s6, s20, 4
	s_lshl_b64 s[40:41], s[16:17], 7
	s_lshl_b64 s[42:43], s[16:17], 12
	s_and_b32 s17, s6, 0xc0
	s_cmp_lt_u32 s7, 2
	s_cselect_b64 s[10:11], -1, 0
	s_add_i32 s6, s22, 64
	s_mov_b32 s7, s23
	s_lshl_b64 s[44:45], s[6:7], 7
	s_lshl_b64 s[46:47], s[6:7], 12
	s_add_i32 s6, s14, 64
	s_lshl_b64 s[48:49], s[6:7], 7
	s_lshl_b64 s[50:51], s[6:7], 12
	s_add_i32 s6, s16, 64
	s_lshl_b32 s84, s3, 10
	s_lshl_b64 s[52:53], s[6:7], 7
	s_lshl_b64 s[54:55], s[6:7], 12
	s_cmp_lt_u32 s18, 8
	s_cselect_b64 s[6:7], -1, 0
	v_cndmask_b32_e64 v8, v11, v14, s[8:9]
	v_cndmask_b32_e64 v9, v10, v13, s[8:9]
	s_and_b64 s[8:9], s[6:7], exec
	s_cselect_b32 s86, 12, 7
	s_and_b64 s[8:9], s[4:5], exec
	s_cselect_b32 s87, 12, 7
	s_cmp_lt_u32 s20, 8
	s_cselect_b64 s[8:9], -1, 0
	v_cndmask_b32_e32 v6, v11, v14, vcc
	v_cndmask_b32_e32 v7, v10, v13, vcc
	v_cndmask_b32_e64 v11, v11, v14, s[10:11]
	v_cndmask_b32_e64 v10, v10, v13, s[10:11]
	s_and_b64 s[10:11], s[8:9], exec
	s_cselect_b32 s88, 12, 7
	s_add_u32 s10, s12, s24
	s_addc_u32 s11, s13, s25
	s_add_u32 s89, s16, 0x80
	v_or_b32_e32 v13, 4, v3
	s_addc_u32 s90, 0, 0
	v_bitop3_b32 v13, v5, v13, v12 bitop3:0x36
	v_or_b32_e32 v3, 6, v3
	s_add_u32 s91, s14, 0x80
	v_lshlrev_b32_e32 v216, 4, v13
	v_bitop3_b32 v3, v5, v3, v12 bitop3:0x36
	v_lshlrev_b32_e32 v12, 1, v4
	v_mov_b32_e32 v13, v2
	s_addc_u32 s92, 0, 0
	v_cndmask_b32_e64 v6, v7, v6, s[6:7]
	v_mov_b32_e32 v7, v2
	v_cndmask_b32_e64 v8, v9, v8, s[4:5]
	v_mov_b32_e32 v9, v2
	v_cndmask_b32_e64 v10, v10, v11, s[8:9]
	v_mov_b32_e32 v11, v2
	v_lshlrev_b32_e32 v217, 4, v3
	v_lshl_add_u64 v[12:13], s[10:11], 0, v[12:13]
	s_mov_b64 s[10:11], 0x31480000
	s_add_u32 s93, s22, 0x80
	v_mbcnt_lo_u32_b32 v3, -1, 0
	v_writelane_b32 v254, s0, 22
	s_mul_i32 s85, s59, 0xc00
	v_lshl_add_u64 v[168:169], v[12:13], 0, s[10:11]
	s_mov_b64 s[56:57], 0x80
	s_addc_u32 s94, 0, 0
	v_lshlrev_b32_e32 v170, 1, v4
	v_mov_b32_e32 v171, v2
	s_mov_b64 s[58:59], 0x40000
	s_lshl_b32 s95, s19, 1
	s_lshl_b32 s96, s15, 1
	s_lshl_b32 s97, s17, 1
	v_lshlrev_b64 v[172:173], 1, v[6:7]
	v_lshlrev_b64 v[174:175], 1, v[8:9]
	v_lshlrev_b64 v[176:177], 1, v[10:11]
	v_mbcnt_hi_u32_b32 v218, -1, v3
	v_mov_b32_e32 v219, 0x1800
	v_writelane_b32 v254, s1, 23
	s_branch .LBB0_1405

.LBB0_1489:
	s_cmp_lt_i32 s84, 22
	s_cselect_b64 s[4:5], -1, 0
	s_cmp_gt_i32 s85, 21
	s_cselect_b64 s[6:7], -1, 0
	s_and_b64 s[4:5], s[4:5], s[6:7]
	s_andn2_b64 vcc, exec, s[4:5]
	s_cbranch_vccnz .LBB0_1594
	v_readfirstlane_b32 s98, v0
	s_nop 3
	s_bitcmp1_b32 s98, 8
	s_cbranch_scc0 .Lsprio_skip_22
	s_setprio 1
.Lsprio_skip_22:
	s_and_b32 s0, s2, 7
	s_ashr_i32 s1, s33, 6
	s_mul_i32 s0, s1, s0
	s_ashr_i32 s1, s2, 6
	s_add_i32 s8, s0, s1
	s_mov_b64 s[10:11], s[70:71]
	s_mov_b64 s[12:13], s[70:71]
	s_mov_b64 s[4:5], s[70:71]
	s_mov_b64 s[6:7], s[70:71]
	s_mov_b64 s[22:23], s[70:71]
	s_mov_b64 s[24:25], s[70:71]
	s_mov_b64 s[26:27], s[70:71]
	s_mov_b64 s[28:29], s[70:71]
	s_mov_b64 s[30:31], s[70:71]
	s_mov_b64 s[34:35], s[70:71]
	s_mov_b64 s[36:37], s[70:71]
	s_cmp_gt_i32 s8, 63
	v_readfirstlane_b32 s3, v0
	s_cbranch_scc1 .LBB0_1540
	s_load_dwordx2 s[14:15], s[10:11], 0xb8
	s_load_dwordx2 s[18:19], s[12:13], 0xb8
	v_lshlrev_b32_e32 v210, 4, v0
	v_lshrrev_b32_e32 v2, 5, v0
	v_lshrrev_b32_e32 v4, 1, v0
	v_and_b32_e32 v2, 4, v2
	v_bfe_u32 v3, v0, 2, 2
	v_and_b32_e32 v4, 24, v4
	v_or_b32_e32 v10, 0x2000, v210
	s_waitcnt lgkmcnt(0)
	s_add_u32 s52, s14, 0x26000000
	v_or3_b32 v2, v2, v3, v4
	v_lshrrev_b32_e32 v3, 7, v10
	s_movk_i32 s0, 0x60
	s_addc_u32 s53, s15, 0
	s_lshr_b32 s16, s3, 6
	s_bfe_u32 s14, s2, 0x30003
	v_and_or_b32 v4, v3, s0, v2
	v_bfe_u32 v13, v0, 2, 4
	s_movk_i32 s0, 0x70
	s_ashr_i32 s9, s8, 31
	s_lshr_b32 s15, s3, 8
	s_lshl_b32 s54, s16, 10
	v_and_b32_e32 v5, 32, v0
	v_and_or_b32 v3, v3, s0, v13
	s_lshl_b64 s[12:13], s[8:9], 20
	s_lshl_b32 s0, s14, 20
	v_bitop3_b32 v11, v210, v5, 48 bitop3:0x6c
	v_and_b32_e32 v12, 64, v0
	s_add_u32 s0, s18, s0
	v_or_b32_e32 v5, v11, v12
	s_addc_u32 s1, s19, 0
	v_lshl_or_b32 v148, v3, 12, v5
	v_lshrrev_b32_e32 v3, 3, v0
	s_add_u32 s10, s0, 0x17800000
	v_and_or_b32 v2, v3, 32, v2
	s_addc_u32 s11, s1, 0
	s_add_i32 s9, s54, 0
	v_lshl_or_b32 v150, v2, 12, v5
	s_add_i32 m0, s9, 0x10000
	v_lshl_or_b32 v146, v4, 12, v5
	global_load_lds_dwordx4 v150, s[10:11]
	s_add_i32 m0, s9, 0x12000
	s_add_u32 s18, s0, 0x17880000
	global_load_lds_dwordx4 v146, s[10:11]
	s_addc_u32 s19, s1, 0
	s_add_i32 m0, s9, 0x14000
	v_and_or_b32 v2, v3, 48, v13
	global_load_lds_dwordx4 v150, s[18:19]
	s_add_i32 m0, s9, 0x16000
	s_add_u32 s12, s52, s12
	s_addc_u32 s13, s53, s13
	s_add_i32 s55, s9, 0x2000
	v_lshl_or_b32 v152, v2, 12, v5
	global_load_lds_dwordx4 v146, s[18:19]
	s_mov_b32 m0, s9
	s_add_u32 s18, s12, 0x80000
	global_load_lds_dwordx4 v152, s[12:13]
	s_mov_b32 m0, s55
	s_addc_u32 s19, s13, 0
	s_add_i32 s56, s9, 0x4000
	global_load_lds_dwordx4 v148, s[12:13]
	s_mov_b32 m0, s56
	s_add_i32 s57, s9, 0x6000
	global_load_lds_dwordx4 v152, s[18:19]
	s_mov_b32 m0, s57
	v_mov_b32_e32 v151, 0
	global_load_lds_dwordx4 v148, s[18:19]
	s_load_dwordx2 s[42:43], s[4:5], 0xb0
	s_load_dwordx2 s[38:39], s[6:7], 0xb0
	s_load_dwordx2 s[44:45], s[22:23], 0xb8
	s_nop 0
	s_load_dwordx2 s[6:7], s[24:25], 0xb8
	s_load_dwordx2 s[4:5], s[26:27], 0xb8
	s_load_dwordx2 s[22:23], s[28:29], 0xb8
	s_load_dwordx2 s[40:41], s[30:31], 0xb8
	s_nop 0
	s_load_dwordx2 s[34:35], s[34:35], 0xb8
	s_nop 0
	s_load_dwordx2 s[30:31], s[36:37], 0xb8
	v_mov_b32_e32 v147, v151
	v_mov_b32_e32 v153, v151
	v_mov_b32_e32 v149, v151
	s_cmp_eq_u32 s15, 1
	s_mov_b32 s58, 0
	v_lshl_add_u64 v[8:9], s[10:11], 0, v[150:151]
	v_lshl_add_u64 v[6:7], s[10:11], 0, v[146:147]
	v_lshl_add_u64 v[2:3], s[12:13], 0, v[152:153]
	s_cselect_b64 s[24:25], -1, 0
	s_cmp_lg_u32 s15, 1
	v_lshl_add_u64 v[4:5], s[12:13], 0, v[148:149]
	s_cbranch_scc1 .LBB0_1493
	s_barrier

.LBB0_1594:
	s_cmp_lt_i32 s84, 24
	s_cselect_b64 s[4:5], -1, 0
	s_cmp_gt_i32 s85, 23
	s_cselect_b64 s[6:7], -1, 0
	s_and_b64 s[4:5], s[4:5], s[6:7]
	s_andn2_b64 vcc, exec, s[4:5]
	s_cbranch_vccnz .LBB0_1665
	v_readfirstlane_b32 s98, v0
	s_nop 3
	s_bitcmp1_b32 s98, 8
	s_cbranch_scc0 .Lsprio_skip_24
	s_setprio 1
.Lsprio_skip_24:
	s_mov_b64 s[6:7], s[70:71]
	s_mov_b64 s[8:9], s[70:71]
	s_mov_b64 s[4:5], s[70:71]
	s_cmpk_gt_i32 s2, 0xaff
	v_readfirstlane_b32 s13, v0
	s_cbranch_scc1 .LBB0_1611
	s_load_dwordx2 s[10:11], s[6:7], 0xb8
	s_load_dwordx2 s[14:15], s[8:9], 0xb8
	v_lshrrev_b32_e32 v2, 5, v0
	v_lshrrev_b32_e32 v4, 1, v0
	v_and_b32_e32 v2, 4, v2
	v_bfe_u32 v3, v0, 2, 2
	v_and_b32_e32 v13, 24, v4
	s_waitcnt lgkmcnt(0)
	s_add_u32 s40, s10, 0x18000000
	v_or3_b32 v2, v2, v3, v13
	v_lshlrev_b32_e32 v3, 4, v0
	s_addc_u32 s41, s11, 0
	v_or_b32_e32 v10, 0x2000, v3
	s_add_u32 s42, s14, 0xa800000
	v_lshrrev_b32_e32 v4, 7, v10
	s_movk_i32 s0, 0x60
	s_addc_u32 s43, s15, 0
	v_and_or_b32 v5, v4, s0, v2
	v_bfe_u32 v14, v0, 2, 4
	s_movk_i32 s0, 0x70
	s_ashr_i32 s45, s2, 31
	v_and_or_b32 v4, v4, s0, v14
	s_lshr_b32 s0, s45, 29
	s_add_i32 s0, s2, s0
	s_lshr_b32 s3, s13, 6
	s_ashr_i32 s1, s0, 3
	s_and_b32 s0, s0, -8
	s_lshr_b32 s14, s13, 8
	s_lshl_b32 s44, s3, 10
	s_sub_i32 s0, s2, s0
	s_cmp_lt_i32 s0, 0
	s_movk_i32 s46, 0x161
	s_cselect_b32 s6, s46, 0x160
	s_mul_i32 s0, s0, s6
	s_add_i32 s0, s0, s1
	s_mul_hi_i32 s1, s0, 0x2e8ba2e9
	s_lshr_b32 s6, s1, 31
	s_ashr_i32 s1, s1, 6
	s_add_i32 s1, s1, s6
	s_lshl_b32 s7, s1, 3
	s_mulk_i32 s1, 0x160
	s_sub_i32 s0, s0, s1
	s_bfe_u32 s1, s0, 0x3001c
	s_add_i32 s1, s0, s1
	s_sext_i32_i16 s6, s1
	s_and_b32 s1, s1, 0xfff8
	s_sub_i32 s0, s0, s1
	s_sext_i32_i16 s0, s0
	v_and_b32_e32 v6, 32, v0
	s_lshr_b32 s12, s6, 3
	s_add_i32 s30, s7, s0
	v_bitop3_b32 v11, v3, v6, 48 bitop3:0x6c
	v_and_b32_e32 v12, 64, v0
	s_ashr_i32 s31, s30, 31
	s_bfe_i64 s[8:9], s[12:13], 0x100000
	v_or_b32_e32 v3, v11, v12
	s_lshl_b64 s[6:7], s[30:31], 20
	s_lshl_b64 s[8:9], s[8:9], 20
	v_lshl_or_b32 v132, v4, 12, v3
	v_lshrrev_b32_e32 v4, 3, v0
	s_add_u32 s36, s42, s8
	v_and_or_b32 v2, v4, 32, v2
	s_addc_u32 s37, s43, s9
	s_add_i32 s31, s44, 0
	v_lshl_or_b32 v134, v2, 12, v3
	s_add_i32 m0, s31, 0x10000
	v_lshl_or_b32 v130, v5, 12, v3
	global_load_lds_dwordx4 v134, s[36:37]
	s_add_i32 m0, s31, 0x12000
	s_add_u32 s8, s36, 0x80000
	global_load_lds_dwordx4 v130, s[36:37]
	s_addc_u32 s9, s37, 0
	s_add_i32 m0, s31, 0x14000
	v_and_or_b32 v2, v4, 48, v14
	global_load_lds_dwordx4 v134, s[8:9]
	s_add_i32 m0, s31, 0x16000
	s_add_u32 s34, s40, s6
	s_addc_u32 s35, s41, s7
	s_add_i32 s47, s31, 0x2000
	v_lshl_or_b32 v136, v2, 12, v3
	global_load_lds_dwordx4 v130, s[8:9]
	s_mov_b32 m0, s31
	s_add_u32 s6, s34, 0x80000
	global_load_lds_dwordx4 v136, s[34:35]
	s_mov_b32 m0, s47
	s_addc_u32 s7, s35, 0
	s_add_i32 s48, s31, 0x4000
	global_load_lds_dwordx4 v132, s[34:35]
	s_mov_b32 m0, s48
	s_add_i32 s49, s31, 0x6000
	global_load_lds_dwordx4 v136, s[6:7]
	s_mov_b32 m0, s49
	s_load_dwordx2 s[4:5], s[4:5], 0xb8
	global_load_lds_dwordx4 v132, s[6:7]
	v_mov_b32_e32 v135, 0
	v_mov_b32_e32 v131, v135
	v_mov_b32_e32 v137, v135
	v_mov_b32_e32 v133, v135
	s_cmp_eq_u32 s14, 1
	s_mov_b32 s50, 0
	v_lshl_add_u64 v[8:9], s[36:37], 0, v[134:135]
	v_lshl_add_u64 v[6:7], s[36:37], 0, v[130:131]
	v_lshl_add_u64 v[2:3], s[34:35], 0, v[136:137]
	s_cselect_b64 s[6:7], -1, 0
	s_cmp_lg_u32 s14, 1
	v_lshl_add_u64 v[4:5], s[34:35], 0, v[132:133]
	s_cbranch_scc1 .LBB0_1598
	s_barrier

.LBB0_1665:
	s_cmp_lt_i32 s84, 25
	s_cselect_b64 s[4:5], -1, 0
	s_cmp_gt_i32 s85, 24
	s_cselect_b64 s[6:7], -1, 0
	s_and_b64 s[4:5], s[4:5], s[6:7]
	s_andn2_b64 vcc, exec, s[4:5]
	s_cbranch_vccnz .LBB0_1718
	v_readfirstlane_b32 s98, v0
	s_nop 3
	s_bitcmp1_b32 s98, 8
	s_cbranch_scc0 .Lsprio_skip_25
	s_setprio 1
.Lsprio_skip_25:
	s_and_b32 s0, s2, 7
	s_ashr_i32 s1, s33, 6
	s_mul_i32 s44, s1, s0
	s_ashr_i32 s0, s2, 6
	s_add_i32 s44, s44, s0
	s_mov_b64 s[4:5], s[70:71]
	s_mov_b64 s[6:7], s[70:71]
	s_mov_b64 s[8:9], s[70:71]
	s_mov_b64 s[10:11], s[70:71]
	s_mov_b64 s[12:13], s[70:71]
	s_mov_b64 s[18:19], s[70:71]
	s_mov_b64 s[14:15], s[70:71]
	s_mov_b64 s[20:21], s[70:71]
	s_cmp_gt_i32 s44, 63
	v_readfirstlane_b32 s36, v0
	s_cbranch_scc1 .LBB0_1718
	v_lshrrev_b32_e32 v2, 5, v0
	v_lshrrev_b32_e32 v4, 1, v0
	v_and_b32_e32 v2, 4, v2
	v_bfe_u32 v3, v0, 2, 2
	v_and_b32_e32 v4, 24, v4
	v_lshlrev_b32_e32 v188, 4, v0
	v_or3_b32 v2, v2, v3, v4
	v_bfe_u32 v3, v0, 3, 25
	s_waitcnt lgkmcnt(0)
	v_and_b32_e32 v5, 32, v0
	v_or_b32_e32 v3, 64, v3
	s_movk_i32 s0, 0x60
	v_bitop3_b32 v10, v188, v5, 48 bitop3:0x6c
	v_and_b32_e32 v11, 64, v0
	s_load_dwordx2 s[22:23], s[4:5], 0xb8
	s_load_dwordx2 s[16:17], s[6:7], 0xb8
	v_and_or_b32 v4, v3, s0, v2
	v_or_b32_e32 v5, v10, v11
	v_mul_u32_u24_e32 v4, 0x1600, v4
	v_lshrrev_b32_e32 v5, 1, v5
	v_or_b32_e32 v4, v4, v5
	v_lshlrev_b32_e32 v130, 1, v4
	v_bfe_u32 v4, v0, 2, 4
	s_movk_i32 s0, 0x70
	s_waitcnt lgkmcnt(0)
	s_add_u32 s45, s22, 0x20000000
	v_and_or_b32 v3, v3, s0, v4
	s_addc_u32 s46, s23, 0
	s_lshr_b32 s40, s36, 6
	s_bfe_u32 s37, s2, 0x30003
	v_mul_u32_u24_e32 v12, 0x1600, v3
	s_lshr_b32 s39, s36, 8
	s_lshl_b32 s47, s40, 10
	v_or_b32_e32 v3, v12, v5
	s_mul_i32 s38, s37, 0x2c0000
	v_lshlrev_b32_e32 v132, 1, v3
	v_lshrrev_b32_e32 v3, 3, v0
	s_add_u32 s2, s16, s38
	v_and_or_b32 v2, v3, 32, v2
	s_addc_u32 s3, s17, 0
	v_mul_u32_u24_e32 v2, 0x1600, v2
	s_add_u32 s4, s2, 0x11600000
	v_or_b32_e32 v2, v2, v5
	s_addc_u32 s5, s3, 0
	s_add_i32 s48, s47, 0
	v_lshlrev_b32_e32 v134, 1, v2
	s_add_i32 m0, s48, 0x10000
	v_and_or_b32 v2, v3, 48, v4
	global_load_lds_dwordx4 v134, s[4:5]
	s_add_i32 m0, s48, 0x12000
	s_add_u32 s2, s2, 0x11760000
	global_load_lds_dwordx4 v130, s[4:5]
	s_addc_u32 s3, s3, 0
	s_add_i32 m0, s48, 0x14000
	s_mul_i32 s1, s44, 0x2c0000
	global_load_lds_dwordx4 v134, s[2:3]
	s_add_i32 m0, s48, 0x16000
	v_mul_u32_u24_e32 v13, 0x1600, v2
	s_mul_hi_i32 s0, s44, 0x2c0000
	s_add_u32 s30, s45, s1
	v_or_b32_e32 v2, v5, v13
	s_addc_u32 s31, s46, s0
	s_add_i32 s49, s48, 0x2000
	v_lshlrev_b32_e32 v136, 1, v2
	global_load_lds_dwordx4 v130, s[2:3]
	s_mov_b32 m0, s48
	s_add_u32 s2, s30, 0x160000
	global_load_lds_dwordx4 v136, s[30:31]
	s_mov_b32 m0, s49
	s_addc_u32 s3, s31, 0
	s_add_i32 s50, s48, 0x4000
	global_load_lds_dwordx4 v132, s[30:31]
	s_mov_b32 m0, s50
	s_add_i32 s51, s48, 0x6000
	global_load_lds_dwordx4 v136, s[2:3]
	s_mov_b32 m0, s51
	v_mov_b32_e32 v135, 0
	global_load_lds_dwordx4 v132, s[2:3]
	s_load_dwordx2 s[26:27], s[8:9], 0xb0
	s_load_dwordx2 s[22:23], s[10:11], 0xb0
	s_load_dwordx2 s[28:29], s[12:13], 0xb8
	s_load_dwordx2 s[34:35], s[18:19], 0xb8
	s_load_dwordx2 s[2:3], s[14:15], 0xb8
	s_load_dwordx2 s[6:7], s[20:21], 0xb8
	s_load_dwordx2 s[24:25], s[70:71], 0xa8
	v_mov_b32_e32 v131, v135
	v_mov_b32_e32 v137, v135
	v_mov_b32_e32 v133, v135
	s_cmp_eq_u32 s39, 1
	s_mov_b32 s52, 0
	v_lshl_add_u64 v[8:9], s[4:5], 0, v[134:135]
	v_lshl_add_u64 v[6:7], s[4:5], 0, v[130:131]
	v_lshl_add_u64 v[4:5], s[30:31], 0, v[136:137]
	v_lshl_add_u64 v[2:3], s[30:31], 0, v[132:133]
	s_cselect_b64 s[8:9], -1, 0
	s_cmp_lg_u32 s39, 1
	s_mov_b64 s[10:11], 0x160000
	s_cbranch_scc1 .LBB0_1669
	s_barrier

	.amdhsa_kernel _Z6mk_fwd4Args
		.amdhsa_group_segment_fixed_size 0
		.amdhsa_private_segment_fixed_size 0
		.amdhsa_kernarg_size 456
		.amdhsa_user_sgpr_count 2
		.amdhsa_user_sgpr_dispatch_ptr 0
		.amdhsa_user_sgpr_queue_ptr 0
		.amdhsa_user_sgpr_kernarg_segment_ptr 1
		.amdhsa_user_sgpr_dispatch_id 0
		.amdhsa_user_sgpr_kernarg_preload_length 0
		.amdhsa_user_sgpr_kernarg_preload_offset 0
		.amdhsa_user_sgpr_private_segment_size 0
		.amdhsa_uses_dynamic_stack 0
		.amdhsa_enable_private_segment 0
		.amdhsa_system_sgpr_workgroup_id_x 1
		.amdhsa_system_sgpr_workgroup_id_y 0
		.amdhsa_system_sgpr_workgroup_id_z 0
		.amdhsa_system_sgpr_workgroup_info 0
		.amdhsa_system_vgpr_workitem_id 0
		.amdhsa_next_free_vgpr 255
		.amdhsa_next_free_sgpr 99
		.amdhsa_accum_offset 256
		.amdhsa_reserve_vcc 1
		.amdhsa_float_round_mode_32 0
		.amdhsa_float_round_mode_16_64 0
		.amdhsa_float_denorm_mode_32 3
		.amdhsa_float_denorm_mode_16_64 3
		.amdhsa_dx10_clamp 1
		.amdhsa_ieee_mode 1
		.amdhsa_fp16_overflow 0
		.amdhsa_tg_split 0
		.amdhsa_exception_fp_ieee_invalid_op 0
		.amdhsa_exception_fp_denorm_src 0
		.amdhsa_exception_fp_ieee_div_zero 0
		.amdhsa_exception_fp_ieee_overflow 0
		.amdhsa_exception_fp_ieee_underflow 0
		.amdhsa_exception_fp_ieee_inexact 0
		.amdhsa_exception_int_div_zero 0
	.end_amdhsa_kernel

amdhsa.kernels:
  - .agpr_count:     0
    .args:
      - .offset:         0
        .size:           200
        .value_kind:     by_value
      - .offset:         200
        .size:           4
        .value_kind:     hidden_block_count_x
      - .offset:         204
        .size:           4
        .value_kind:     hidden_block_count_y
      - .offset:         208
        .size:           4
        .value_kind:     hidden_block_count_z
      - .offset:         212
        .size:           2
        .value_kind:     hidden_group_size_x
      - .offset:         214
        .size:           2
        .value_kind:     hidden_group_size_y
      - .offset:         216
        .size:           2
        .value_kind:     hidden_group_size_z
      - .offset:         218
        .size:           2
        .value_kind:     hidden_remainder_x
      - .offset:         220
        .size:           2
        .value_kind:     hidden_remainder_y
      - .offset:         222
        .size:           2
        .value_kind:     hidden_remainder_z
      - .offset:         240
        .size:           8
        .value_kind:     hidden_global_offset_x
      - .offset:         248
        .size:           8
        .value_kind:     hidden_global_offset_y
      - .offset:         256
        .size:           8
        .value_kind:     hidden_global_offset_z
      - .offset:         264
        .size:           2
        .value_kind:     hidden_grid_dims
      - .offset:         320
        .size:           4
        .value_kind:     hidden_dynamic_lds_size
    .group_segment_fixed_size: 0
    .kernarg_segment_align: 8
    .kernarg_segment_size: 456
    .language:       OpenCL C
    .language_version:
      - 2
      - 0
    .max_flat_workgroup_size: 512
    .name:           _Z6mk_fwd4Args
    .private_segment_fixed_size: 0
    .sgpr_count:     105
    .sgpr_spill_count: 24
    .symbol:         _Z6mk_fwd4Args.kd
    .uniform_work_group_size: 1
    .uses_dynamic_stack: false
    .vgpr_count:     255
    .vgpr_spill_count: 0
    .wavefront_size: 64
